# v14: v13 + post-barrier lgkmcnt(0) at the 48 GEMM MMA-segment heads hoisted to before the barrier (wave parks there anyway)
# baseline (speedup 1.0000x reference)
.LBB0_237:
	ds_read_b128 v[128:131], v169
	ds_read_b128 v[152:155], v169 offset:1024
	ds_read_b128 v[156:159], v169 offset:2048
	ds_read_b128 v[160:163], v169 offset:3072
	s_add_u32 s20, s8, 0xfff80080
	s_addc_u32 s21, s9, -1
	s_cmp_eq_u32 s35, 28
	s_cselect_b32 s21, s1, s21
	s_cselect_b32 s20, s7, s20
	s_cselect_b32 s79, s22, s34
	s_cselect_b32 s78, s23, s33
	v_lshl_add_u64 v[164:165], s[8:9], 0, v[142:143]
	s_add_i32 m0, s12, 0xc000
	ds_read_b128 v[172:175], v170
	ds_read_b128 v[176:179], v170 offset:1024
	ds_read_b128 v[180:183], v170 offset:2048
	ds_read_b128 v[184:187], v170 offset:3072
	ds_read_b128 v[188:191], v170 offset:4096
	ds_read_b128 v[194:197], v170 offset:5120
	ds_read_b128 v[198:201], v170 offset:6144
	ds_read_b128 v[202:205], v170 offset:7168
	global_load_lds_dwordx4 v[164:165], off
	s_add_i32 m0, s12, 0xe000
	v_lshl_add_u64 v[164:165], s[8:9], 0, v[146:147]
	global_load_lds_dwordx4 v[164:165], off
	s_waitcnt lgkmcnt(8)
	s_waitcnt lgkmcnt(0)
	s_barrier
	s_setprio 1
	v_mfma_f32_16x16x32_bf16 v[124:127], v[128:131], v[172:175], v[124:127]
	v_mfma_f32_16x16x32_bf16 v[120:123], v[156:159], v[172:175], v[120:123]
	v_mfma_f32_16x16x32_bf16 v[108:111], v[128:131], v[180:183], v[108:111]
	v_mfma_f32_16x16x32_bf16 v[104:107], v[156:159], v[180:183], v[104:107]
	v_mfma_f32_16x16x32_bf16 v[92:95], v[128:131], v[188:191], v[92:95]
	v_mfma_f32_16x16x32_bf16 v[88:91], v[156:159], v[188:191], v[88:91]
	v_mfma_f32_16x16x32_bf16 v[76:79], v[128:131], v[198:201], v[76:79]
	v_mfma_f32_16x16x32_bf16 v[72:75], v[156:159], v[198:201], v[72:75]
	v_mfma_f32_16x16x32_bf16 v[124:127], v[152:155], v[176:179], v[124:127]
	v_mfma_f32_16x16x32_bf16 v[120:123], v[160:163], v[176:179], v[120:123]
	v_mfma_f32_16x16x32_bf16 v[108:111], v[152:155], v[184:187], v[108:111]
	v_mfma_f32_16x16x32_bf16 v[104:107], v[160:163], v[184:187], v[104:107]
	v_mfma_f32_16x16x32_bf16 v[92:95], v[152:155], v[194:197], v[92:95]
	v_mfma_f32_16x16x32_bf16 v[88:91], v[160:163], v[194:197], v[88:91]
	v_mfma_f32_16x16x32_bf16 v[76:79], v[152:155], v[202:205], v[76:79]
	v_mfma_f32_16x16x32_bf16 v[72:75], v[160:163], v[202:205], v[72:75]
	s_setprio 0
	s_barrier
	s_add_i32 s50, s82, s11
	v_lshl_add_u64 v[164:165], s[78:79], 0, v[134:135]
	s_mov_b32 m0, s50
	ds_read_b128 v[206:209], v171
	ds_read_b128 v[210:213], v171 offset:1024
	ds_read_b128 v[214:217], v171 offset:2048
	ds_read_b128 v[218:221], v171 offset:3072
	global_load_lds_dwordx4 v[164:165], off
	s_add_i32 m0, s50, 0x2000
	v_lshl_add_u64 v[222:223], s[78:79], 0, v[138:139]
	global_load_lds_dwordx4 v[222:223], off
	s_waitcnt lgkmcnt(0)
	s_barrier
	s_setprio 1
	v_mfma_f32_16x16x32_bf16 v[116:119], v[206:209], v[172:175], v[116:119]
	v_mfma_f32_16x16x32_bf16 v[112:115], v[214:217], v[172:175], v[112:115]
	v_mfma_f32_16x16x32_bf16 v[100:103], v[206:209], v[180:183], v[100:103]
	v_mfma_f32_16x16x32_bf16 v[96:99], v[214:217], v[180:183], v[96:99]
	v_mfma_f32_16x16x32_bf16 v[84:87], v[206:209], v[188:191], v[84:87]
	v_mfma_f32_16x16x32_bf16 v[80:83], v[214:217], v[188:191], v[80:83]
	v_mfma_f32_16x16x32_bf16 v[68:71], v[206:209], v[198:201], v[68:71]
	v_mfma_f32_16x16x32_bf16 v[64:67], v[214:217], v[198:201], v[64:67]
	v_mfma_f32_16x16x32_bf16 v[116:119], v[210:213], v[176:179], v[116:119]
	v_mfma_f32_16x16x32_bf16 v[112:115], v[218:221], v[176:179], v[112:115]
	v_mfma_f32_16x16x32_bf16 v[100:103], v[210:213], v[184:187], v[100:103]
	v_mfma_f32_16x16x32_bf16 v[96:99], v[218:221], v[184:187], v[96:99]
	v_mfma_f32_16x16x32_bf16 v[84:87], v[210:213], v[194:197], v[84:87]
	v_mfma_f32_16x16x32_bf16 v[80:83], v[218:221], v[194:197], v[80:83]
	v_mfma_f32_16x16x32_bf16 v[68:71], v[210:213], v[202:205], v[68:71]
	v_mfma_f32_16x16x32_bf16 v[64:67], v[218:221], v[202:205], v[64:67]
	s_setprio 0
	s_mov_b32 m0, s12
	v_lshl_add_u64 v[224:225], s[20:21], 0, v[132:133]
	s_barrier
	ds_read_b128 v[172:175], v170 offset:16384
	ds_read_b128 v[176:179], v170 offset:17408
	ds_read_b128 v[180:183], v170 offset:18432
	ds_read_b128 v[184:187], v170 offset:19456
	ds_read_b128 v[188:191], v170 offset:20480
	ds_read_b128 v[194:197], v170 offset:21504
	ds_read_b128 v[198:201], v170 offset:22528
	ds_read_b128 v[202:205], v170 offset:23552
	global_load_lds_dwordx4 v[224:225], off
	s_mov_b32 m0, s36
	v_lshl_add_u64 v[226:227], s[20:21], 0, v[136:137]
	global_load_lds_dwordx4 v[226:227], off
	s_waitcnt lgkmcnt(0)
	s_barrier
	s_setprio 1
	v_mfma_f32_16x16x32_bf16 v[60:63], v[128:131], v[172:175], v[60:63]
	v_mfma_f32_16x16x32_bf16 v[56:59], v[156:159], v[172:175], v[56:59]
	v_mfma_f32_16x16x32_bf16 v[44:47], v[128:131], v[180:183], v[44:47]
	v_mfma_f32_16x16x32_bf16 v[40:43], v[156:159], v[180:183], v[40:43]
	v_mfma_f32_16x16x32_bf16 v[28:31], v[128:131], v[188:191], v[28:31]
	v_mfma_f32_16x16x32_bf16 v[24:27], v[156:159], v[188:191], v[24:27]
	v_mfma_f32_16x16x32_bf16 v[12:15], v[128:131], v[198:201], v[12:15]
	v_mfma_f32_16x16x32_bf16 v[8:11], v[156:159], v[198:201], v[8:11]
	v_mfma_f32_16x16x32_bf16 v[60:63], v[152:155], v[176:179], v[60:63]
	v_mfma_f32_16x16x32_bf16 v[56:59], v[160:163], v[176:179], v[56:59]
	v_mfma_f32_16x16x32_bf16 v[44:47], v[152:155], v[184:187], v[44:47]
	v_mfma_f32_16x16x32_bf16 v[40:43], v[160:163], v[184:187], v[40:43]
	v_mfma_f32_16x16x32_bf16 v[28:31], v[152:155], v[194:197], v[28:31]
	v_mfma_f32_16x16x32_bf16 v[24:27], v[160:163], v[194:197], v[24:27]
	v_mfma_f32_16x16x32_bf16 v[12:15], v[152:155], v[202:205], v[12:15]
	v_mfma_f32_16x16x32_bf16 v[8:11], v[160:163], v[202:205], v[8:11]
	s_setprio 0
	s_barrier
	s_add_u32 s50, s78, 0x80000
	s_addc_u32 s51, s79, 0
	s_add_i32 s58, s84, s11
	s_mov_b32 m0, s58
	v_lshl_add_u64 v[128:129], s[50:51], 0, v[134:135]
	global_load_lds_dwordx4 v[128:129], off
	s_add_i32 m0, s58, 0x2000
	v_lshl_add_u64 v[128:129], s[50:51], 0, v[138:139]
	global_load_lds_dwordx4 v[128:129], off
	s_waitcnt vmcnt(6)
	s_barrier
	s_setprio 1
	v_mfma_f32_16x16x32_bf16 v[52:55], v[206:209], v[172:175], v[52:55]
	v_mfma_f32_16x16x32_bf16 v[48:51], v[214:217], v[172:175], v[48:51]
	v_mfma_f32_16x16x32_bf16 v[36:39], v[206:209], v[180:183], v[36:39]
	v_mfma_f32_16x16x32_bf16 v[32:35], v[214:217], v[180:183], v[32:35]
	v_mfma_f32_16x16x32_bf16 v[20:23], v[206:209], v[188:191], v[20:23]
	v_mfma_f32_16x16x32_bf16 v[16:19], v[214:217], v[188:191], v[16:19]
	v_mfma_f32_16x16x32_bf16 v[4:7], v[206:209], v[198:201], v[4:7]
	v_mfma_f32_16x16x32_bf16 v[0:3], v[214:217], v[198:201], v[0:3]
	v_mfma_f32_16x16x32_bf16 v[52:55], v[210:213], v[176:179], v[52:55]
	v_mfma_f32_16x16x32_bf16 v[48:51], v[218:221], v[176:179], v[48:51]
	v_mfma_f32_16x16x32_bf16 v[36:39], v[210:213], v[184:187], v[36:39]
	v_mfma_f32_16x16x32_bf16 v[32:35], v[218:221], v[184:187], v[32:35]
	v_mfma_f32_16x16x32_bf16 v[20:23], v[210:213], v[194:197], v[20:23]
	v_mfma_f32_16x16x32_bf16 v[16:19], v[218:221], v[194:197], v[16:19]
	v_mfma_f32_16x16x32_bf16 v[4:7], v[210:213], v[202:205], v[4:7]
	v_mfma_f32_16x16x32_bf16 v[0:3], v[218:221], v[202:205], v[0:3]
	s_setprio 0
	s_add_i32 s50, 0, 0x18000
	v_add_u32_e32 v140, s50, v167
	s_barrier
	ds_read_b128 v[128:131], v140
	ds_read_b128 v[152:155], v140 offset:1024
	ds_read_b128 v[156:159], v140 offset:2048
	ds_read_b128 v[160:163], v140 offset:3072
	s_add_u32 s20, s20, 0x80000
	s_addc_u32 s21, s21, 0
	s_mov_b32 m0, s37
	v_lshl_add_u64 v[206:207], s[20:21], 0, v[132:133]
	ds_read_b128 v[172:175], v170 offset:32768
	ds_read_b128 v[176:179], v170 offset:33792
	ds_read_b128 v[180:183], v170 offset:34816
	ds_read_b128 v[184:187], v170 offset:35840
	ds_read_b128 v[188:191], v170 offset:36864
	ds_read_b128 v[194:197], v170 offset:37888
	ds_read_b128 v[198:201], v170 offset:38912
	ds_read_b128 v[202:205], v170 offset:39936
	global_load_lds_dwordx4 v[206:207], off
	s_mov_b32 m0, s38
	v_lshl_add_u64 v[206:207], s[20:21], 0, v[136:137]
	global_load_lds_dwordx4 v[206:207], off
	s_waitcnt lgkmcnt(8)
	s_waitcnt lgkmcnt(0)
	s_barrier
	s_setprio 1
	v_mfma_f32_16x16x32_bf16 v[124:127], v[128:131], v[172:175], v[124:127]
	v_mfma_f32_16x16x32_bf16 v[120:123], v[156:159], v[172:175], v[120:123]
	v_mfma_f32_16x16x32_bf16 v[108:111], v[128:131], v[180:183], v[108:111]
	v_mfma_f32_16x16x32_bf16 v[104:107], v[156:159], v[180:183], v[104:107]
	v_mfma_f32_16x16x32_bf16 v[92:95], v[128:131], v[188:191], v[92:95]
	v_mfma_f32_16x16x32_bf16 v[88:91], v[156:159], v[188:191], v[88:91]
	v_mfma_f32_16x16x32_bf16 v[76:79], v[128:131], v[198:201], v[76:79]
	v_mfma_f32_16x16x32_bf16 v[72:75], v[156:159], v[198:201], v[72:75]
	v_mfma_f32_16x16x32_bf16 v[124:127], v[152:155], v[176:179], v[124:127]
	v_mfma_f32_16x16x32_bf16 v[120:123], v[160:163], v[176:179], v[120:123]
	v_mfma_f32_16x16x32_bf16 v[108:111], v[152:155], v[184:187], v[108:111]
	v_mfma_f32_16x16x32_bf16 v[104:107], v[160:163], v[184:187], v[104:107]
	v_mfma_f32_16x16x32_bf16 v[92:95], v[152:155], v[194:197], v[92:95]
	v_mfma_f32_16x16x32_bf16 v[88:91], v[160:163], v[194:197], v[88:91]
	v_mfma_f32_16x16x32_bf16 v[76:79], v[152:155], v[202:205], v[76:79]
	v_mfma_f32_16x16x32_bf16 v[72:75], v[160:163], v[202:205], v[72:75]
	s_setprio 0
	s_barrier
	s_add_i32 s51, 0, 0x1c000
	s_add_i32 s20, s50, s11
	v_add_u32_e32 v140, s51, v167
	v_lshl_add_u64 v[164:165], v[164:165], 0, s[18:19]
	s_mov_b32 m0, s20
	ds_read_b128 v[206:209], v140
	ds_read_b128 v[210:213], v140 offset:1024
	ds_read_b128 v[214:217], v140 offset:2048
	ds_read_b128 v[218:221], v140 offset:3072
	global_load_lds_dwordx4 v[164:165], off
	s_add_i32 m0, s20, 0x2000
	v_lshl_add_u64 v[164:165], v[222:223], 0, s[18:19]
	global_load_lds_dwordx4 v[164:165], off
	s_waitcnt lgkmcnt(0)
	s_barrier
	s_setprio 1
	v_mfma_f32_16x16x32_bf16 v[116:119], v[206:209], v[172:175], v[116:119]
	v_mfma_f32_16x16x32_bf16 v[112:115], v[214:217], v[172:175], v[112:115]
	v_mfma_f32_16x16x32_bf16 v[100:103], v[206:209], v[180:183], v[100:103]
	v_mfma_f32_16x16x32_bf16 v[96:99], v[214:217], v[180:183], v[96:99]
	v_mfma_f32_16x16x32_bf16 v[84:87], v[206:209], v[188:191], v[84:87]
	v_mfma_f32_16x16x32_bf16 v[80:83], v[214:217], v[188:191], v[80:83]
	v_mfma_f32_16x16x32_bf16 v[68:71], v[206:209], v[198:201], v[68:71]
	v_mfma_f32_16x16x32_bf16 v[64:67], v[214:217], v[198:201], v[64:67]
	v_mfma_f32_16x16x32_bf16 v[116:119], v[210:213], v[176:179], v[116:119]
	v_mfma_f32_16x16x32_bf16 v[112:115], v[218:221], v[176:179], v[112:115]
	v_mfma_f32_16x16x32_bf16 v[100:103], v[210:213], v[184:187], v[100:103]
	v_mfma_f32_16x16x32_bf16 v[96:99], v[218:221], v[184:187], v[96:99]
	v_mfma_f32_16x16x32_bf16 v[84:87], v[210:213], v[194:197], v[84:87]
	v_mfma_f32_16x16x32_bf16 v[80:83], v[218:221], v[194:197], v[80:83]
	v_mfma_f32_16x16x32_bf16 v[68:71], v[210:213], v[202:205], v[68:71]
	v_mfma_f32_16x16x32_bf16 v[64:67], v[218:221], v[202:205], v[64:67]
	s_setprio 0
	s_mov_b32 m0, s57
	v_lshl_add_u64 v[164:165], v[224:225], 0, s[18:19]
	s_barrier
	ds_read_b128 v[172:175], v170 offset:49152
	ds_read_b128 v[176:179], v170 offset:50176
	ds_read_b128 v[180:183], v170 offset:51200
	ds_read_b128 v[184:187], v170 offset:52224
	ds_read_b128 v[188:191], v170 offset:53248
	ds_read_b128 v[194:197], v170 offset:54272
	ds_read_b128 v[198:201], v170 offset:55296
	ds_read_b128 v[202:205], v170 offset:56320
	global_load_lds_dwordx4 v[164:165], off
	s_mov_b32 m0, s80
	v_lshl_add_u64 v[164:165], v[226:227], 0, s[18:19]
	global_load_lds_dwordx4 v[164:165], off
	s_waitcnt lgkmcnt(0)
	s_barrier
	s_setprio 1
	v_mfma_f32_16x16x32_bf16 v[60:63], v[128:131], v[172:175], v[60:63]
	v_mfma_f32_16x16x32_bf16 v[56:59], v[156:159], v[172:175], v[56:59]
	v_mfma_f32_16x16x32_bf16 v[44:47], v[128:131], v[180:183], v[44:47]
	v_mfma_f32_16x16x32_bf16 v[40:43], v[156:159], v[180:183], v[40:43]
	v_mfma_f32_16x16x32_bf16 v[28:31], v[128:131], v[188:191], v[28:31]
	v_mfma_f32_16x16x32_bf16 v[24:27], v[156:159], v[188:191], v[24:27]
	v_mfma_f32_16x16x32_bf16 v[12:15], v[128:131], v[198:201], v[12:15]
	v_mfma_f32_16x16x32_bf16 v[8:11], v[156:159], v[198:201], v[8:11]
	v_mfma_f32_16x16x32_bf16 v[60:63], v[152:155], v[176:179], v[60:63]
	v_mfma_f32_16x16x32_bf16 v[56:59], v[160:163], v[176:179], v[56:59]
	v_mfma_f32_16x16x32_bf16 v[44:47], v[152:155], v[184:187], v[44:47]
	v_mfma_f32_16x16x32_bf16 v[40:43], v[160:163], v[184:187], v[40:43]
	v_mfma_f32_16x16x32_bf16 v[28:31], v[152:155], v[194:197], v[28:31]
	v_mfma_f32_16x16x32_bf16 v[24:27], v[160:163], v[194:197], v[24:27]
	v_mfma_f32_16x16x32_bf16 v[12:15], v[152:155], v[202:205], v[12:15]
	v_mfma_f32_16x16x32_bf16 v[8:11], v[160:163], v[202:205], v[8:11]
	s_setprio 0
	s_barrier
	s_add_u32 s20, s78, 0x80080
	s_addc_u32 s21, s79, 0
	s_add_i32 s50, s51, s11
	s_mov_b32 m0, s50
	v_lshl_add_u64 v[128:129], s[20:21], 0, v[134:135]
	global_load_lds_dwordx4 v[128:129], off
	s_add_i32 m0, s50, 0x2000
	v_lshl_add_u64 v[128:129], s[20:21], 0, v[138:139]
	global_load_lds_dwordx4 v[128:129], off
	s_waitcnt vmcnt(6)
	s_barrier
	s_setprio 1
	v_mfma_f32_16x16x32_bf16 v[52:55], v[206:209], v[172:175], v[52:55]
	v_mfma_f32_16x16x32_bf16 v[48:51], v[214:217], v[172:175], v[48:51]
	v_mfma_f32_16x16x32_bf16 v[36:39], v[206:209], v[180:183], v[36:39]
	v_mfma_f32_16x16x32_bf16 v[32:35], v[214:217], v[180:183], v[32:35]
	v_mfma_f32_16x16x32_bf16 v[20:23], v[206:209], v[188:191], v[20:23]
	v_mfma_f32_16x16x32_bf16 v[16:19], v[214:217], v[188:191], v[16:19]
	v_mfma_f32_16x16x32_bf16 v[4:7], v[206:209], v[198:201], v[4:7]
	v_mfma_f32_16x16x32_bf16 v[0:3], v[214:217], v[198:201], v[0:3]
	v_mfma_f32_16x16x32_bf16 v[52:55], v[210:213], v[176:179], v[52:55]
	v_mfma_f32_16x16x32_bf16 v[48:51], v[218:221], v[176:179], v[48:51]
	v_mfma_f32_16x16x32_bf16 v[36:39], v[210:213], v[184:187], v[36:39]
	v_mfma_f32_16x16x32_bf16 v[32:35], v[218:221], v[184:187], v[32:35]
	v_mfma_f32_16x16x32_bf16 v[20:23], v[210:213], v[194:197], v[20:23]
	v_mfma_f32_16x16x32_bf16 v[16:19], v[218:221], v[194:197], v[16:19]
	v_mfma_f32_16x16x32_bf16 v[4:7], v[210:213], v[202:205], v[4:7]
	v_mfma_f32_16x16x32_bf16 v[0:3], v[218:221], v[202:205], v[0:3]
	s_setprio 0
	s_add_i32 s35, s35, 2
	s_add_u32 s8, s8, 0x100
	s_addc_u32 s9, s9, 0
	s_add_u32 s33, s33, 0x100
	s_addc_u32 s34, s34, 0
	s_cmp_gt_u32 s35, 29
	s_barrier
	s_cbranch_scc0 .LBB0_237
	s_lshl_b32 s65, s6, 8
	v_lshl_add_u32 v154, s0, 8, v166
	v_or_b32_e32 v152, s65, v168
	v_ashrrev_i32_e32 v155, 31, v154
	v_lshlrev_b64 v[162:163], 7, v[154:155]
	v_lshlrev_b64 v[160:161], 11, v[154:155]
	v_mad_i64_i32 v[158:159], s[0:1], v154, s85, 0
	v_cmp_gt_i32_e64 s[8:9], s39, v154
	v_lshlrev_b64 v[156:157], 12, v[154:155]
	v_cvt_pk_bf16_f32 v128, v124, v125
	v_cvt_pk_bf16_f32 v129, v126, v127
	v_cvt_pk_bf16_f32 v130, v120, v121
	v_cvt_pk_bf16_f32 v131, v122, v123
	v_cmp_lt_i32_e64 s[6:7], s86, v152
	s_and_saveexec_b64 s[0:1], s[6:7]
	s_xor_b64 s[0:1], exec, s[0:1]
	s_cbranch_execz .LBB0_255
	s_cmpk_gt_u32 s65, 0xbff
	s_mov_b64 s[20:21], -1
	s_cbranch_scc0 .LBB0_251
	s_cmpk_gt_u32 s65, 0x17ff
	s_cbranch_scc0 .LBB0_248
	s_cmpk_gt_u32 s65, 0x1bff
	s_cbranch_scc0 .LBB0_245
	v_cmp_gt_u32_e32 vcc, s87, v152
	s_and_saveexec_b64 s[20:21], vcc
	s_cbranch_execz .LBB0_244
	v_readlane_b32 s22, v254, 24
	v_readlane_b32 s23, v254, 25
	v_mov_b32_e32 v153, v141
	s_nop 0
	v_lshl_add_u64 v[164:165], s[22:23], 0, v[162:163]
	v_lshl_add_u64 v[164:165], v[152:153], 2, v[164:165]
	v_add_co_u32_e32 v172, vcc, 0xffff9000, v164
	s_nop 1
	v_addc_co_u32_e32 v173, vcc, -1, v165, vcc
	v_add_co_u32_e32 v164, vcc, 0xffffa000, v164
	global_store_dwordx4 v[172:173], v[124:127], off
	s_nop 0
	v_addc_co_u32_e32 v165, vcc, -1, v165, vcc
	global_store_dwordx4 v[164:165], v[120:123], off offset:-4080

.LBB0_912:
	ds_read_b128 v[150:153], v161
	ds_read_b128 v[154:157], v161 offset:1024
	ds_read_b128 v[164:167], v161 offset:2048
	ds_read_b128 v[168:171], v161 offset:3072
	s_add_u32 s20, s48, 0xfff80080
	s_addc_u32 s21, s49, -1
	s_cmp_eq_u32 s47, 28
	s_cselect_b32 s21, s17, s21
	s_cselect_b32 s20, s33, s20
	s_cselect_b32 s51, s15, s45
	s_cselect_b32 s50, s34, s35
	v_lshl_add_u64 v[208:209], s[48:49], 0, v[138:139]
	s_add_i32 m0, s36, 0xc000
	ds_read_b128 v[172:175], v162
	ds_read_b128 v[176:179], v162 offset:1024
	ds_read_b128 v[180:183], v162 offset:2048
	ds_read_b128 v[184:187], v162 offset:3072
	ds_read_b128 v[188:191], v162 offset:4096
	ds_read_b128 v[196:199], v162 offset:5120
	ds_read_b128 v[200:203], v162 offset:6144
	ds_read_b128 v[204:207], v162 offset:7168
	global_load_lds_dwordx4 v[208:209], off
	s_add_i32 m0, s36, 0xe000
	v_lshl_add_u64 v[208:209], s[48:49], 0, v[140:141]
	global_load_lds_dwordx4 v[208:209], off
	s_waitcnt lgkmcnt(8)
	s_waitcnt lgkmcnt(0)
	s_barrier
	s_setprio 1
	v_mfma_f32_16x16x32_bf16 v[124:127], v[150:153], v[172:175], v[124:127]
	v_mfma_f32_16x16x32_bf16 v[120:123], v[164:167], v[172:175], v[120:123]
	v_mfma_f32_16x16x32_bf16 v[108:111], v[150:153], v[180:183], v[108:111]
	v_mfma_f32_16x16x32_bf16 v[104:107], v[164:167], v[180:183], v[104:107]
	v_mfma_f32_16x16x32_bf16 v[92:95], v[150:153], v[188:191], v[92:95]
	v_mfma_f32_16x16x32_bf16 v[88:91], v[164:167], v[188:191], v[88:91]
	v_mfma_f32_16x16x32_bf16 v[76:79], v[150:153], v[200:203], v[76:79]
	v_mfma_f32_16x16x32_bf16 v[72:75], v[164:167], v[200:203], v[72:75]
	v_mfma_f32_16x16x32_bf16 v[124:127], v[154:157], v[176:179], v[124:127]
	v_mfma_f32_16x16x32_bf16 v[120:123], v[168:171], v[176:179], v[120:123]
	v_mfma_f32_16x16x32_bf16 v[108:111], v[154:157], v[184:187], v[108:111]
	v_mfma_f32_16x16x32_bf16 v[104:107], v[168:171], v[184:187], v[104:107]
	v_mfma_f32_16x16x32_bf16 v[92:95], v[154:157], v[196:199], v[92:95]
	v_mfma_f32_16x16x32_bf16 v[88:91], v[168:171], v[196:199], v[88:91]
	v_mfma_f32_16x16x32_bf16 v[76:79], v[154:157], v[204:207], v[76:79]
	v_mfma_f32_16x16x32_bf16 v[72:75], v[168:171], v[204:207], v[72:75]
	s_setprio 0
	s_barrier
	s_add_i32 s65, s62, s23
	v_lshl_add_u64 v[224:225], s[50:51], 0, v[130:131]
	s_mov_b32 m0, s65
	ds_read_b128 v[208:211], v163
	ds_read_b128 v[212:215], v163 offset:1024
	ds_read_b128 v[216:219], v163 offset:2048
	ds_read_b128 v[220:223], v163 offset:3072
	global_load_lds_dwordx4 v[224:225], off
	s_add_i32 m0, s65, 0x2000
	v_lshl_add_u64 v[226:227], s[50:51], 0, v[134:135]
	global_load_lds_dwordx4 v[226:227], off
	s_waitcnt lgkmcnt(0)
	s_barrier
	s_setprio 1
	v_mfma_f32_16x16x32_bf16 v[116:119], v[208:211], v[172:175], v[116:119]
	v_mfma_f32_16x16x32_bf16 v[112:115], v[216:219], v[172:175], v[112:115]
	v_mfma_f32_16x16x32_bf16 v[100:103], v[208:211], v[180:183], v[100:103]
	v_mfma_f32_16x16x32_bf16 v[96:99], v[216:219], v[180:183], v[96:99]
	v_mfma_f32_16x16x32_bf16 v[84:87], v[208:211], v[188:191], v[84:87]
	v_mfma_f32_16x16x32_bf16 v[80:83], v[216:219], v[188:191], v[80:83]
	v_mfma_f32_16x16x32_bf16 v[68:71], v[208:211], v[200:203], v[68:71]
	v_mfma_f32_16x16x32_bf16 v[64:67], v[216:219], v[200:203], v[64:67]
	v_mfma_f32_16x16x32_bf16 v[116:119], v[212:215], v[176:179], v[116:119]
	v_mfma_f32_16x16x32_bf16 v[112:115], v[220:223], v[176:179], v[112:115]
	v_mfma_f32_16x16x32_bf16 v[100:103], v[212:215], v[184:187], v[100:103]
	v_mfma_f32_16x16x32_bf16 v[96:99], v[220:223], v[184:187], v[96:99]
	v_mfma_f32_16x16x32_bf16 v[84:87], v[212:215], v[196:199], v[84:87]
	v_mfma_f32_16x16x32_bf16 v[80:83], v[220:223], v[196:199], v[80:83]
	v_mfma_f32_16x16x32_bf16 v[68:71], v[212:215], v[204:207], v[68:71]
	v_mfma_f32_16x16x32_bf16 v[64:67], v[220:223], v[204:207], v[64:67]
	s_setprio 0
	s_mov_b32 m0, s36
	v_lshl_add_u64 v[228:229], s[20:21], 0, v[128:129]
	s_barrier
	ds_read_b128 v[172:175], v162 offset:16384
	ds_read_b128 v[176:179], v162 offset:17408
	ds_read_b128 v[180:183], v162 offset:18432
	ds_read_b128 v[184:187], v162 offset:19456
	ds_read_b128 v[188:191], v162 offset:20480
	ds_read_b128 v[196:199], v162 offset:21504
	ds_read_b128 v[200:203], v162 offset:22528
	ds_read_b128 v[204:207], v162 offset:23552
	global_load_lds_dwordx4 v[228:229], off
	s_mov_b32 m0, s37
	v_lshl_add_u64 v[230:231], s[20:21], 0, v[132:133]
	global_load_lds_dwordx4 v[230:231], off
	s_waitcnt lgkmcnt(0)
	s_barrier
	s_setprio 1
	v_mfma_f32_16x16x32_bf16 v[60:63], v[150:153], v[172:175], v[60:63]
	v_mfma_f32_16x16x32_bf16 v[56:59], v[164:167], v[172:175], v[56:59]
	v_mfma_f32_16x16x32_bf16 v[44:47], v[150:153], v[180:183], v[44:47]
	v_mfma_f32_16x16x32_bf16 v[40:43], v[164:167], v[180:183], v[40:43]
	v_mfma_f32_16x16x32_bf16 v[28:31], v[150:153], v[188:191], v[28:31]
	v_mfma_f32_16x16x32_bf16 v[24:27], v[164:167], v[188:191], v[24:27]
	v_mfma_f32_16x16x32_bf16 v[12:15], v[150:153], v[200:203], v[12:15]
	v_mfma_f32_16x16x32_bf16 v[8:11], v[164:167], v[200:203], v[8:11]
	v_mfma_f32_16x16x32_bf16 v[60:63], v[154:157], v[176:179], v[60:63]
	v_mfma_f32_16x16x32_bf16 v[56:59], v[168:171], v[176:179], v[56:59]
	v_mfma_f32_16x16x32_bf16 v[44:47], v[154:157], v[184:187], v[44:47]
	v_mfma_f32_16x16x32_bf16 v[40:43], v[168:171], v[184:187], v[40:43]
	v_mfma_f32_16x16x32_bf16 v[28:31], v[154:157], v[196:199], v[28:31]
	v_mfma_f32_16x16x32_bf16 v[24:27], v[168:171], v[196:199], v[24:27]
	v_mfma_f32_16x16x32_bf16 v[12:15], v[154:157], v[204:207], v[12:15]
	v_mfma_f32_16x16x32_bf16 v[8:11], v[168:171], v[204:207], v[8:11]
	s_setprio 0
	s_barrier
	s_add_u32 s66, s50, 0x80000
	s_addc_u32 s67, s51, 0
	s_add_i32 s65, s63, s23
	s_mov_b32 m0, s65
	v_lshl_add_u64 v[150:151], s[66:67], 0, v[130:131]
	global_load_lds_dwordx4 v[150:151], off
	s_add_i32 m0, s65, 0x2000
	v_lshl_add_u64 v[150:151], s[66:67], 0, v[134:135]
	global_load_lds_dwordx4 v[150:151], off
	s_waitcnt vmcnt(6)
	s_barrier
	s_setprio 1
	v_mfma_f32_16x16x32_bf16 v[52:55], v[208:211], v[172:175], v[52:55]
	v_mfma_f32_16x16x32_bf16 v[48:51], v[216:219], v[172:175], v[48:51]
	v_mfma_f32_16x16x32_bf16 v[36:39], v[208:211], v[180:183], v[36:39]
	v_mfma_f32_16x16x32_bf16 v[32:35], v[216:219], v[180:183], v[32:35]
	v_mfma_f32_16x16x32_bf16 v[20:23], v[208:211], v[188:191], v[20:23]
	v_mfma_f32_16x16x32_bf16 v[16:19], v[216:219], v[188:191], v[16:19]
	v_mfma_f32_16x16x32_bf16 v[4:7], v[208:211], v[200:203], v[4:7]
	v_mfma_f32_16x16x32_bf16 v[0:3], v[216:219], v[200:203], v[0:3]
	v_mfma_f32_16x16x32_bf16 v[52:55], v[212:215], v[176:179], v[52:55]
	v_mfma_f32_16x16x32_bf16 v[48:51], v[220:223], v[176:179], v[48:51]
	v_mfma_f32_16x16x32_bf16 v[36:39], v[212:215], v[184:187], v[36:39]
	v_mfma_f32_16x16x32_bf16 v[32:35], v[220:223], v[184:187], v[32:35]
	v_mfma_f32_16x16x32_bf16 v[20:23], v[212:215], v[196:199], v[20:23]
	v_mfma_f32_16x16x32_bf16 v[16:19], v[220:223], v[196:199], v[16:19]
	v_mfma_f32_16x16x32_bf16 v[4:7], v[212:215], v[204:207], v[4:7]
	v_mfma_f32_16x16x32_bf16 v[0:3], v[220:223], v[204:207], v[0:3]
	s_setprio 0
	s_add_i32 s65, 0, 0x18000
	v_add_u32_e32 v136, s65, v158
	s_barrier
	ds_read_b128 v[150:153], v136
	ds_read_b128 v[154:157], v136 offset:1024
	ds_read_b128 v[164:167], v136 offset:2048
	ds_read_b128 v[168:171], v136 offset:3072
	s_add_u32 s20, s20, 0x80000
	s_addc_u32 s21, s21, 0
	s_mov_b32 m0, s38
	v_lshl_add_u64 v[208:209], s[20:21], 0, v[128:129]
	ds_read_b128 v[172:175], v162 offset:32768
	ds_read_b128 v[176:179], v162 offset:33792
	ds_read_b128 v[180:183], v162 offset:34816
	ds_read_b128 v[184:187], v162 offset:35840
	ds_read_b128 v[188:191], v162 offset:36864
	ds_read_b128 v[196:199], v162 offset:37888
	ds_read_b128 v[200:203], v162 offset:38912
	ds_read_b128 v[204:207], v162 offset:39936
	global_load_lds_dwordx4 v[208:209], off
	s_mov_b32 m0, s39
	v_lshl_add_u64 v[208:209], s[20:21], 0, v[132:133]
	global_load_lds_dwordx4 v[208:209], off
	s_waitcnt lgkmcnt(8)
	s_waitcnt lgkmcnt(0)
	s_barrier
	s_setprio 1
	v_mfma_f32_16x16x32_bf16 v[124:127], v[150:153], v[172:175], v[124:127]
	v_mfma_f32_16x16x32_bf16 v[120:123], v[164:167], v[172:175], v[120:123]
	v_mfma_f32_16x16x32_bf16 v[108:111], v[150:153], v[180:183], v[108:111]
	v_mfma_f32_16x16x32_bf16 v[104:107], v[164:167], v[180:183], v[104:107]
	v_mfma_f32_16x16x32_bf16 v[92:95], v[150:153], v[188:191], v[92:95]
	v_mfma_f32_16x16x32_bf16 v[88:91], v[164:167], v[188:191], v[88:91]
	v_mfma_f32_16x16x32_bf16 v[76:79], v[150:153], v[200:203], v[76:79]
	v_mfma_f32_16x16x32_bf16 v[72:75], v[164:167], v[200:203], v[72:75]
	v_mfma_f32_16x16x32_bf16 v[124:127], v[154:157], v[176:179], v[124:127]
	v_mfma_f32_16x16x32_bf16 v[120:123], v[168:171], v[176:179], v[120:123]
	v_mfma_f32_16x16x32_bf16 v[108:111], v[154:157], v[184:187], v[108:111]
	v_mfma_f32_16x16x32_bf16 v[104:107], v[168:171], v[184:187], v[104:107]
	v_mfma_f32_16x16x32_bf16 v[92:95], v[154:157], v[196:199], v[92:95]
	v_mfma_f32_16x16x32_bf16 v[88:91], v[168:171], v[196:199], v[88:91]
	v_mfma_f32_16x16x32_bf16 v[76:79], v[154:157], v[204:207], v[76:79]
	v_mfma_f32_16x16x32_bf16 v[72:75], v[168:171], v[204:207], v[72:75]
	s_setprio 0
	s_barrier
	s_add_i32 s66, 0, 0x1c000
	s_add_i32 s20, s65, s23
	v_add_u32_e32 v136, s66, v158
	v_lshl_add_u64 v[224:225], v[224:225], 0, s[10:11]
	s_mov_b32 m0, s20
	ds_read_b128 v[208:211], v136
	ds_read_b128 v[212:215], v136 offset:1024
	ds_read_b128 v[216:219], v136 offset:2048
	ds_read_b128 v[220:223], v136 offset:3072
	global_load_lds_dwordx4 v[224:225], off
	s_add_i32 m0, s20, 0x2000
	v_lshl_add_u64 v[224:225], v[226:227], 0, s[10:11]
	global_load_lds_dwordx4 v[224:225], off
	s_waitcnt lgkmcnt(0)
	s_barrier
	s_setprio 1
	v_mfma_f32_16x16x32_bf16 v[116:119], v[208:211], v[172:175], v[116:119]
	v_mfma_f32_16x16x32_bf16 v[112:115], v[216:219], v[172:175], v[112:115]
	v_mfma_f32_16x16x32_bf16 v[100:103], v[208:211], v[180:183], v[100:103]
	v_mfma_f32_16x16x32_bf16 v[96:99], v[216:219], v[180:183], v[96:99]
	v_mfma_f32_16x16x32_bf16 v[84:87], v[208:211], v[188:191], v[84:87]
	v_mfma_f32_16x16x32_bf16 v[80:83], v[216:219], v[188:191], v[80:83]
	v_mfma_f32_16x16x32_bf16 v[68:71], v[208:211], v[200:203], v[68:71]
	v_mfma_f32_16x16x32_bf16 v[64:67], v[216:219], v[200:203], v[64:67]
	v_mfma_f32_16x16x32_bf16 v[116:119], v[212:215], v[176:179], v[116:119]
	v_mfma_f32_16x16x32_bf16 v[112:115], v[220:223], v[176:179], v[112:115]
	v_mfma_f32_16x16x32_bf16 v[100:103], v[212:215], v[184:187], v[100:103]
	v_mfma_f32_16x16x32_bf16 v[96:99], v[220:223], v[184:187], v[96:99]
	v_mfma_f32_16x16x32_bf16 v[84:87], v[212:215], v[196:199], v[84:87]
	v_mfma_f32_16x16x32_bf16 v[80:83], v[220:223], v[196:199], v[80:83]
	v_mfma_f32_16x16x32_bf16 v[68:71], v[212:215], v[204:207], v[68:71]
	v_mfma_f32_16x16x32_bf16 v[64:67], v[220:223], v[204:207], v[64:67]
	s_setprio 0
	s_mov_b32 m0, s58
	v_lshl_add_u64 v[224:225], v[228:229], 0, s[10:11]
	s_barrier
	ds_read_b128 v[172:175], v162 offset:49152
	ds_read_b128 v[176:179], v162 offset:50176
	ds_read_b128 v[180:183], v162 offset:51200
	ds_read_b128 v[184:187], v162 offset:52224
	ds_read_b128 v[188:191], v162 offset:53248
	ds_read_b128 v[196:199], v162 offset:54272
	ds_read_b128 v[200:203], v162 offset:55296
	ds_read_b128 v[204:207], v162 offset:56320
	global_load_lds_dwordx4 v[224:225], off
	s_mov_b32 m0, s59
	v_lshl_add_u64 v[224:225], v[230:231], 0, s[10:11]
	global_load_lds_dwordx4 v[224:225], off
	s_waitcnt lgkmcnt(0)
	s_barrier
	s_setprio 1
	v_mfma_f32_16x16x32_bf16 v[60:63], v[150:153], v[172:175], v[60:63]
	v_mfma_f32_16x16x32_bf16 v[56:59], v[164:167], v[172:175], v[56:59]
	v_mfma_f32_16x16x32_bf16 v[44:47], v[150:153], v[180:183], v[44:47]
	v_mfma_f32_16x16x32_bf16 v[40:43], v[164:167], v[180:183], v[40:43]
	v_mfma_f32_16x16x32_bf16 v[28:31], v[150:153], v[188:191], v[28:31]
	v_mfma_f32_16x16x32_bf16 v[24:27], v[164:167], v[188:191], v[24:27]
	v_mfma_f32_16x16x32_bf16 v[12:15], v[150:153], v[200:203], v[12:15]
	v_mfma_f32_16x16x32_bf16 v[8:11], v[164:167], v[200:203], v[8:11]
	v_mfma_f32_16x16x32_bf16 v[60:63], v[154:157], v[176:179], v[60:63]
	v_mfma_f32_16x16x32_bf16 v[56:59], v[168:171], v[176:179], v[56:59]
	v_mfma_f32_16x16x32_bf16 v[44:47], v[154:157], v[184:187], v[44:47]
	v_mfma_f32_16x16x32_bf16 v[40:43], v[168:171], v[184:187], v[40:43]
	v_mfma_f32_16x16x32_bf16 v[28:31], v[154:157], v[196:199], v[28:31]
	v_mfma_f32_16x16x32_bf16 v[24:27], v[168:171], v[196:199], v[24:27]
	v_mfma_f32_16x16x32_bf16 v[12:15], v[154:157], v[204:207], v[12:15]
	v_mfma_f32_16x16x32_bf16 v[8:11], v[168:171], v[204:207], v[8:11]
	s_setprio 0
	s_barrier
	s_add_u32 s20, s50, 0x80080
	s_addc_u32 s21, s51, 0
	s_add_i32 s50, s66, s23
	s_mov_b32 m0, s50
	v_lshl_add_u64 v[150:151], s[20:21], 0, v[130:131]
	global_load_lds_dwordx4 v[150:151], off
	s_add_i32 m0, s50, 0x2000
	v_lshl_add_u64 v[150:151], s[20:21], 0, v[134:135]
	global_load_lds_dwordx4 v[150:151], off
	s_waitcnt vmcnt(6)
	s_barrier
	s_setprio 1
	v_mfma_f32_16x16x32_bf16 v[52:55], v[208:211], v[172:175], v[52:55]
	v_mfma_f32_16x16x32_bf16 v[48:51], v[216:219], v[172:175], v[48:51]
	v_mfma_f32_16x16x32_bf16 v[36:39], v[208:211], v[180:183], v[36:39]
	v_mfma_f32_16x16x32_bf16 v[32:35], v[216:219], v[180:183], v[32:35]
	v_mfma_f32_16x16x32_bf16 v[20:23], v[208:211], v[188:191], v[20:23]
	v_mfma_f32_16x16x32_bf16 v[16:19], v[216:219], v[188:191], v[16:19]
	v_mfma_f32_16x16x32_bf16 v[4:7], v[208:211], v[200:203], v[4:7]
	v_mfma_f32_16x16x32_bf16 v[0:3], v[216:219], v[200:203], v[0:3]
	v_mfma_f32_16x16x32_bf16 v[52:55], v[212:215], v[176:179], v[52:55]
	v_mfma_f32_16x16x32_bf16 v[48:51], v[220:223], v[176:179], v[48:51]
	v_mfma_f32_16x16x32_bf16 v[36:39], v[212:215], v[184:187], v[36:39]
	v_mfma_f32_16x16x32_bf16 v[32:35], v[220:223], v[184:187], v[32:35]
	v_mfma_f32_16x16x32_bf16 v[20:23], v[212:215], v[196:199], v[20:23]
	v_mfma_f32_16x16x32_bf16 v[16:19], v[220:223], v[196:199], v[16:19]
	v_mfma_f32_16x16x32_bf16 v[4:7], v[212:215], v[204:207], v[4:7]
	v_mfma_f32_16x16x32_bf16 v[0:3], v[220:223], v[204:207], v[0:3]
	s_setprio 0
	s_add_i32 s47, s47, 2
	s_add_u32 s48, s48, 0x100
	s_addc_u32 s49, s49, 0
	s_add_u32 s35, s35, 0x100
	s_addc_u32 s45, s45, 0
	s_cmp_gt_u32 s47, 29
	s_cbranch_scc1 .Lepi_last_about
	s_barrier
	s_branch .LBB0_912

.LBB0_999:
	ds_read_b128 v[156:159], v152
	ds_read_b128 v[160:163], v152 offset:1024
	ds_read_b128 v[164:167], v152 offset:2048
	ds_read_b128 v[168:171], v152 offset:3072
	s_add_u32 s20, s46, 0xfff80080
	s_addc_u32 s21, s47, -1
	s_cmp_eq_u32 s58, 28
	s_cselect_b32 s21, s15, s21
	s_cselect_b32 s20, s54, s20
	s_cselect_b32 s49, s11, s57
	s_cselect_b32 s48, s55, s56
	v_lshl_add_u64 v[148:149], s[46:47], 0, v[136:137]
	s_add_i32 m0, s35, 0xc000
	ds_read_b128 v[172:175], v153
	ds_read_b128 v[176:179], v153 offset:1024
	ds_read_b128 v[180:183], v153 offset:2048
	ds_read_b128 v[184:187], v153 offset:3072
	ds_read_b128 v[188:191], v153 offset:4096
	ds_read_b128 v[196:199], v153 offset:5120
	ds_read_b128 v[200:203], v153 offset:6144
	ds_read_b128 v[204:207], v153 offset:7168
	global_load_lds_dwordx4 v[148:149], off
	s_add_i32 m0, s35, 0xe000
	v_lshl_add_u64 v[148:149], s[46:47], 0, v[138:139]
	global_load_lds_dwordx4 v[148:149], off
	s_waitcnt lgkmcnt(8)
	s_waitcnt lgkmcnt(0)
	s_barrier
	s_setprio 1
	v_mfma_f32_16x16x32_bf16 v[124:127], v[156:159], v[172:175], v[124:127]
	v_mfma_f32_16x16x32_bf16 v[120:123], v[164:167], v[172:175], v[120:123]
	v_mfma_f32_16x16x32_bf16 v[108:111], v[156:159], v[180:183], v[108:111]
	v_mfma_f32_16x16x32_bf16 v[104:107], v[164:167], v[180:183], v[104:107]
	v_mfma_f32_16x16x32_bf16 v[92:95], v[156:159], v[188:191], v[92:95]
	v_mfma_f32_16x16x32_bf16 v[88:91], v[164:167], v[188:191], v[88:91]
	v_mfma_f32_16x16x32_bf16 v[76:79], v[156:159], v[200:203], v[76:79]
	v_mfma_f32_16x16x32_bf16 v[72:75], v[164:167], v[200:203], v[72:75]
	v_mfma_f32_16x16x32_bf16 v[124:127], v[160:163], v[176:179], v[124:127]
	v_mfma_f32_16x16x32_bf16 v[120:123], v[168:171], v[176:179], v[120:123]
	v_mfma_f32_16x16x32_bf16 v[108:111], v[160:163], v[184:187], v[108:111]
	v_mfma_f32_16x16x32_bf16 v[104:107], v[168:171], v[184:187], v[104:107]
	v_mfma_f32_16x16x32_bf16 v[92:95], v[160:163], v[196:199], v[92:95]
	v_mfma_f32_16x16x32_bf16 v[88:91], v[168:171], v[196:199], v[88:91]
	v_mfma_f32_16x16x32_bf16 v[76:79], v[160:163], v[204:207], v[76:79]
	v_mfma_f32_16x16x32_bf16 v[72:75], v[168:171], v[204:207], v[72:75]
	s_setprio 0
	s_barrier
	s_add_i32 s59, s52, s23
	v_lshl_add_u64 v[148:149], s[48:49], 0, v[132:133]
	s_mov_b32 m0, s59
	ds_read_b128 v[208:211], v154
	ds_read_b128 v[212:215], v154 offset:1024
	ds_read_b128 v[216:219], v154 offset:2048
	ds_read_b128 v[220:223], v154 offset:3072
	global_load_lds_dwordx4 v[148:149], off
	s_add_i32 m0, s59, 0x2000
	v_lshl_add_u64 v[224:225], s[48:49], 0, v[128:129]
	global_load_lds_dwordx4 v[224:225], off
	s_waitcnt lgkmcnt(0)
	s_barrier
	s_setprio 1
	v_mfma_f32_16x16x32_bf16 v[116:119], v[208:211], v[172:175], v[116:119]
	v_mfma_f32_16x16x32_bf16 v[112:115], v[216:219], v[172:175], v[112:115]
	v_mfma_f32_16x16x32_bf16 v[100:103], v[208:211], v[180:183], v[100:103]
	v_mfma_f32_16x16x32_bf16 v[96:99], v[216:219], v[180:183], v[96:99]
	v_mfma_f32_16x16x32_bf16 v[84:87], v[208:211], v[188:191], v[84:87]
	v_mfma_f32_16x16x32_bf16 v[80:83], v[216:219], v[188:191], v[80:83]
	v_mfma_f32_16x16x32_bf16 v[68:71], v[208:211], v[200:203], v[68:71]
	v_mfma_f32_16x16x32_bf16 v[64:67], v[216:219], v[200:203], v[64:67]
	v_mfma_f32_16x16x32_bf16 v[116:119], v[212:215], v[176:179], v[116:119]
	v_mfma_f32_16x16x32_bf16 v[112:115], v[220:223], v[176:179], v[112:115]
	v_mfma_f32_16x16x32_bf16 v[100:103], v[212:215], v[184:187], v[100:103]
	v_mfma_f32_16x16x32_bf16 v[96:99], v[220:223], v[184:187], v[96:99]
	v_mfma_f32_16x16x32_bf16 v[84:87], v[212:215], v[196:199], v[84:87]
	v_mfma_f32_16x16x32_bf16 v[80:83], v[220:223], v[196:199], v[80:83]
	v_mfma_f32_16x16x32_bf16 v[68:71], v[212:215], v[204:207], v[68:71]
	v_mfma_f32_16x16x32_bf16 v[64:67], v[220:223], v[204:207], v[64:67]
	s_setprio 0
	s_mov_b32 m0, s35
	v_lshl_add_u64 v[226:227], s[20:21], 0, v[134:135]
	s_barrier
	ds_read_b128 v[172:175], v153 offset:16384
	ds_read_b128 v[176:179], v153 offset:17408
	ds_read_b128 v[180:183], v153 offset:18432
	ds_read_b128 v[184:187], v153 offset:19456
	ds_read_b128 v[188:191], v153 offset:20480
	ds_read_b128 v[196:199], v153 offset:21504
	ds_read_b128 v[200:203], v153 offset:22528
	ds_read_b128 v[204:207], v153 offset:23552
	global_load_lds_dwordx4 v[226:227], off
	s_mov_b32 m0, s36
	v_lshl_add_u64 v[228:229], s[20:21], 0, v[130:131]
	global_load_lds_dwordx4 v[228:229], off
	s_waitcnt lgkmcnt(0)
	s_barrier
	s_setprio 1
	v_mfma_f32_16x16x32_bf16 v[60:63], v[156:159], v[172:175], v[60:63]
	v_mfma_f32_16x16x32_bf16 v[56:59], v[164:167], v[172:175], v[56:59]
	v_mfma_f32_16x16x32_bf16 v[44:47], v[156:159], v[180:183], v[44:47]
	v_mfma_f32_16x16x32_bf16 v[40:43], v[164:167], v[180:183], v[40:43]
	v_mfma_f32_16x16x32_bf16 v[28:31], v[156:159], v[188:191], v[28:31]
	v_mfma_f32_16x16x32_bf16 v[24:27], v[164:167], v[188:191], v[24:27]
	v_mfma_f32_16x16x32_bf16 v[12:15], v[156:159], v[200:203], v[12:15]
	v_mfma_f32_16x16x32_bf16 v[8:11], v[164:167], v[200:203], v[8:11]
	v_mfma_f32_16x16x32_bf16 v[60:63], v[160:163], v[176:179], v[60:63]
	v_mfma_f32_16x16x32_bf16 v[56:59], v[168:171], v[176:179], v[56:59]
	v_mfma_f32_16x16x32_bf16 v[44:47], v[160:163], v[184:187], v[44:47]
	v_mfma_f32_16x16x32_bf16 v[40:43], v[168:171], v[184:187], v[40:43]
	v_mfma_f32_16x16x32_bf16 v[28:31], v[160:163], v[196:199], v[28:31]
	v_mfma_f32_16x16x32_bf16 v[24:27], v[168:171], v[196:199], v[24:27]
	v_mfma_f32_16x16x32_bf16 v[12:15], v[160:163], v[204:207], v[12:15]
	v_mfma_f32_16x16x32_bf16 v[8:11], v[168:171], v[204:207], v[8:11]
	s_setprio 0
	s_barrier
	s_add_u32 s60, s48, 0x80000
	s_addc_u32 s61, s49, 0
	s_add_i32 s59, s53, s23
	s_mov_b32 m0, s59
	v_lshl_add_u64 v[156:157], s[60:61], 0, v[132:133]
	global_load_lds_dwordx4 v[156:157], off
	s_add_i32 m0, s59, 0x2000
	v_lshl_add_u64 v[156:157], s[60:61], 0, v[128:129]
	global_load_lds_dwordx4 v[156:157], off
	s_waitcnt vmcnt(6)
	s_barrier
	s_setprio 1
	v_mfma_f32_16x16x32_bf16 v[52:55], v[208:211], v[172:175], v[52:55]
	v_mfma_f32_16x16x32_bf16 v[48:51], v[216:219], v[172:175], v[48:51]
	v_mfma_f32_16x16x32_bf16 v[36:39], v[208:211], v[180:183], v[36:39]
	v_mfma_f32_16x16x32_bf16 v[32:35], v[216:219], v[180:183], v[32:35]
	v_mfma_f32_16x16x32_bf16 v[20:23], v[208:211], v[188:191], v[20:23]
	v_mfma_f32_16x16x32_bf16 v[16:19], v[216:219], v[188:191], v[16:19]
	v_mfma_f32_16x16x32_bf16 v[4:7], v[208:211], v[200:203], v[4:7]
	v_mfma_f32_16x16x32_bf16 v[0:3], v[216:219], v[200:203], v[0:3]
	v_mfma_f32_16x16x32_bf16 v[52:55], v[212:215], v[176:179], v[52:55]
	v_mfma_f32_16x16x32_bf16 v[48:51], v[220:223], v[176:179], v[48:51]
	v_mfma_f32_16x16x32_bf16 v[36:39], v[212:215], v[184:187], v[36:39]
	v_mfma_f32_16x16x32_bf16 v[32:35], v[220:223], v[184:187], v[32:35]
	v_mfma_f32_16x16x32_bf16 v[20:23], v[212:215], v[196:199], v[20:23]
	v_mfma_f32_16x16x32_bf16 v[16:19], v[220:223], v[196:199], v[16:19]
	v_mfma_f32_16x16x32_bf16 v[4:7], v[212:215], v[204:207], v[4:7]
	v_mfma_f32_16x16x32_bf16 v[0:3], v[220:223], v[204:207], v[0:3]
	s_setprio 0
	s_add_i32 s59, 0, 0x18000
	v_add_u32_e32 v155, s59, v150
	s_barrier
	ds_read_b128 v[156:159], v155
	ds_read_b128 v[160:163], v155 offset:1024
	ds_read_b128 v[164:167], v155 offset:2048
	ds_read_b128 v[168:171], v155 offset:3072
	s_add_u32 s20, s20, 0x80000
	s_addc_u32 s21, s21, 0
	s_mov_b32 m0, s37
	v_lshl_add_u64 v[208:209], s[20:21], 0, v[134:135]
	ds_read_b128 v[172:175], v153 offset:32768
	ds_read_b128 v[176:179], v153 offset:33792
	ds_read_b128 v[180:183], v153 offset:34816
	ds_read_b128 v[184:187], v153 offset:35840
	ds_read_b128 v[188:191], v153 offset:36864
	ds_read_b128 v[196:199], v153 offset:37888
	ds_read_b128 v[200:203], v153 offset:38912
	ds_read_b128 v[204:207], v153 offset:39936
	global_load_lds_dwordx4 v[208:209], off
	s_mov_b32 m0, s38
	v_lshl_add_u64 v[208:209], s[20:21], 0, v[130:131]
	global_load_lds_dwordx4 v[208:209], off
	s_waitcnt lgkmcnt(8)
	s_waitcnt lgkmcnt(0)
	s_barrier
	s_setprio 1
	v_mfma_f32_16x16x32_bf16 v[124:127], v[156:159], v[172:175], v[124:127]
	v_mfma_f32_16x16x32_bf16 v[120:123], v[164:167], v[172:175], v[120:123]
	v_mfma_f32_16x16x32_bf16 v[108:111], v[156:159], v[180:183], v[108:111]
	v_mfma_f32_16x16x32_bf16 v[104:107], v[164:167], v[180:183], v[104:107]
	v_mfma_f32_16x16x32_bf16 v[92:95], v[156:159], v[188:191], v[92:95]
	v_mfma_f32_16x16x32_bf16 v[88:91], v[164:167], v[188:191], v[88:91]
	v_mfma_f32_16x16x32_bf16 v[76:79], v[156:159], v[200:203], v[76:79]
	v_mfma_f32_16x16x32_bf16 v[72:75], v[164:167], v[200:203], v[72:75]
	v_mfma_f32_16x16x32_bf16 v[124:127], v[160:163], v[176:179], v[124:127]
	v_mfma_f32_16x16x32_bf16 v[120:123], v[168:171], v[176:179], v[120:123]
	v_mfma_f32_16x16x32_bf16 v[108:111], v[160:163], v[184:187], v[108:111]
	v_mfma_f32_16x16x32_bf16 v[104:107], v[168:171], v[184:187], v[104:107]
	v_mfma_f32_16x16x32_bf16 v[92:95], v[160:163], v[196:199], v[92:95]
	v_mfma_f32_16x16x32_bf16 v[88:91], v[168:171], v[196:199], v[88:91]
	v_mfma_f32_16x16x32_bf16 v[76:79], v[160:163], v[204:207], v[76:79]
	v_mfma_f32_16x16x32_bf16 v[72:75], v[168:171], v[204:207], v[72:75]
	s_setprio 0
	s_barrier
	s_add_i32 s60, 0, 0x1c000
	s_add_i32 s20, s59, s23
	v_add_u32_e32 v155, s60, v150
	v_lshl_add_u64 v[148:149], v[148:149], 0, s[8:9]
	s_mov_b32 m0, s20
	ds_read_b128 v[208:211], v155
	ds_read_b128 v[212:215], v155 offset:1024
	ds_read_b128 v[216:219], v155 offset:2048
	ds_read_b128 v[220:223], v155 offset:3072
	global_load_lds_dwordx4 v[148:149], off
	s_add_i32 m0, s20, 0x2000
	v_lshl_add_u64 v[148:149], v[224:225], 0, s[8:9]
	global_load_lds_dwordx4 v[148:149], off
	s_waitcnt lgkmcnt(0)
	s_barrier
	s_setprio 1
	v_mfma_f32_16x16x32_bf16 v[116:119], v[208:211], v[172:175], v[116:119]
	v_mfma_f32_16x16x32_bf16 v[112:115], v[216:219], v[172:175], v[112:115]
	v_mfma_f32_16x16x32_bf16 v[100:103], v[208:211], v[180:183], v[100:103]
	v_mfma_f32_16x16x32_bf16 v[96:99], v[216:219], v[180:183], v[96:99]
	v_mfma_f32_16x16x32_bf16 v[84:87], v[208:211], v[188:191], v[84:87]
	v_mfma_f32_16x16x32_bf16 v[80:83], v[216:219], v[188:191], v[80:83]
	v_mfma_f32_16x16x32_bf16 v[68:71], v[208:211], v[200:203], v[68:71]
	v_mfma_f32_16x16x32_bf16 v[64:67], v[216:219], v[200:203], v[64:67]
	v_mfma_f32_16x16x32_bf16 v[116:119], v[212:215], v[176:179], v[116:119]
	v_mfma_f32_16x16x32_bf16 v[112:115], v[220:223], v[176:179], v[112:115]
	v_mfma_f32_16x16x32_bf16 v[100:103], v[212:215], v[184:187], v[100:103]
	v_mfma_f32_16x16x32_bf16 v[96:99], v[220:223], v[184:187], v[96:99]
	v_mfma_f32_16x16x32_bf16 v[84:87], v[212:215], v[196:199], v[84:87]
	v_mfma_f32_16x16x32_bf16 v[80:83], v[220:223], v[196:199], v[80:83]
	v_mfma_f32_16x16x32_bf16 v[68:71], v[212:215], v[204:207], v[68:71]
	v_mfma_f32_16x16x32_bf16 v[64:67], v[220:223], v[204:207], v[64:67]
	s_setprio 0
	s_mov_b32 m0, s45
	v_lshl_add_u64 v[148:149], v[226:227], 0, s[8:9]
	s_barrier
	ds_read_b128 v[172:175], v153 offset:49152
	ds_read_b128 v[176:179], v153 offset:50176
	ds_read_b128 v[180:183], v153 offset:51200
	ds_read_b128 v[184:187], v153 offset:52224
	ds_read_b128 v[188:191], v153 offset:53248
	ds_read_b128 v[196:199], v153 offset:54272
	ds_read_b128 v[200:203], v153 offset:55296
	ds_read_b128 v[204:207], v153 offset:56320
	global_load_lds_dwordx4 v[148:149], off
	s_mov_b32 m0, s50
	v_lshl_add_u64 v[148:149], v[228:229], 0, s[8:9]
	global_load_lds_dwordx4 v[148:149], off
	s_waitcnt lgkmcnt(0)
	s_barrier
	s_setprio 1
	v_mfma_f32_16x16x32_bf16 v[60:63], v[156:159], v[172:175], v[60:63]
	v_mfma_f32_16x16x32_bf16 v[56:59], v[164:167], v[172:175], v[56:59]
	v_mfma_f32_16x16x32_bf16 v[44:47], v[156:159], v[180:183], v[44:47]
	v_mfma_f32_16x16x32_bf16 v[40:43], v[164:167], v[180:183], v[40:43]
	v_mfma_f32_16x16x32_bf16 v[28:31], v[156:159], v[188:191], v[28:31]
	v_mfma_f32_16x16x32_bf16 v[24:27], v[164:167], v[188:191], v[24:27]
	v_mfma_f32_16x16x32_bf16 v[12:15], v[156:159], v[200:203], v[12:15]
	v_mfma_f32_16x16x32_bf16 v[8:11], v[164:167], v[200:203], v[8:11]
	v_mfma_f32_16x16x32_bf16 v[60:63], v[160:163], v[176:179], v[60:63]
	v_mfma_f32_16x16x32_bf16 v[56:59], v[168:171], v[176:179], v[56:59]
	v_mfma_f32_16x16x32_bf16 v[44:47], v[160:163], v[184:187], v[44:47]
	v_mfma_f32_16x16x32_bf16 v[40:43], v[168:171], v[184:187], v[40:43]
	v_mfma_f32_16x16x32_bf16 v[28:31], v[160:163], v[196:199], v[28:31]
	v_mfma_f32_16x16x32_bf16 v[24:27], v[168:171], v[196:199], v[24:27]
	v_mfma_f32_16x16x32_bf16 v[12:15], v[160:163], v[204:207], v[12:15]
	v_mfma_f32_16x16x32_bf16 v[8:11], v[168:171], v[204:207], v[8:11]
	s_setprio 0
	s_barrier
	s_add_u32 s20, s48, 0x80080
	s_addc_u32 s21, s49, 0
	s_add_i32 s48, s60, s23
	s_mov_b32 m0, s48
	v_lshl_add_u64 v[148:149], s[20:21], 0, v[132:133]
	global_load_lds_dwordx4 v[148:149], off
	s_add_i32 m0, s48, 0x2000
	v_lshl_add_u64 v[148:149], s[20:21], 0, v[128:129]
	global_load_lds_dwordx4 v[148:149], off
	s_waitcnt vmcnt(6)
	s_barrier
	s_setprio 1
	v_mfma_f32_16x16x32_bf16 v[52:55], v[208:211], v[172:175], v[52:55]
	v_mfma_f32_16x16x32_bf16 v[48:51], v[216:219], v[172:175], v[48:51]
	v_mfma_f32_16x16x32_bf16 v[36:39], v[208:211], v[180:183], v[36:39]
	v_mfma_f32_16x16x32_bf16 v[32:35], v[216:219], v[180:183], v[32:35]
	v_mfma_f32_16x16x32_bf16 v[20:23], v[208:211], v[188:191], v[20:23]
	v_mfma_f32_16x16x32_bf16 v[16:19], v[216:219], v[188:191], v[16:19]
	v_mfma_f32_16x16x32_bf16 v[4:7], v[208:211], v[200:203], v[4:7]
	v_mfma_f32_16x16x32_bf16 v[0:3], v[216:219], v[200:203], v[0:3]
	v_mfma_f32_16x16x32_bf16 v[52:55], v[212:215], v[176:179], v[52:55]
	v_mfma_f32_16x16x32_bf16 v[48:51], v[220:223], v[176:179], v[48:51]
	v_mfma_f32_16x16x32_bf16 v[36:39], v[212:215], v[184:187], v[36:39]
	v_mfma_f32_16x16x32_bf16 v[32:35], v[220:223], v[184:187], v[32:35]
	v_mfma_f32_16x16x32_bf16 v[20:23], v[212:215], v[196:199], v[20:23]
	v_mfma_f32_16x16x32_bf16 v[16:19], v[220:223], v[196:199], v[16:19]
	v_mfma_f32_16x16x32_bf16 v[4:7], v[212:215], v[204:207], v[4:7]
	v_mfma_f32_16x16x32_bf16 v[0:3], v[220:223], v[204:207], v[0:3]
	s_setprio 0
	s_add_i32 s58, s58, 2
	s_add_u32 s46, s46, 0x100
	s_addc_u32 s47, s47, 0
	s_add_u32 s56, s56, 0x100
	s_addc_u32 s57, s57, 0
	s_cmp_gt_u32 s58, 29
	s_cbranch_scc1 .Ldup_last_mlpin0
	s_barrier
	s_branch .LBB0_999

.LBB0_1030:
	ds_read_b128 v[148:151], v159
	ds_read_b128 v[152:155], v159 offset:1024
	ds_read_b128 v[162:165], v159 offset:2048
	ds_read_b128 v[166:169], v159 offset:3072
	s_add_u32 s20, s48, 0xffe00080
	s_addc_u32 s21, s49, -1
	s_cmpk_eq_i32 s63, 0x7c
	s_cselect_b32 s21, s17, s21
	s_cselect_b32 s20, s59, s20
	s_cselect_b32 s51, s15, s62
	s_cselect_b32 s50, s60, s61
	v_lshl_add_u64 v[190:191], s[48:49], 0, v[136:137]
	s_add_i32 m0, s37, 0xc000
	ds_read_b128 v[170:173], v160
	ds_read_b128 v[174:177], v160 offset:1024
	ds_read_b128 v[178:181], v160 offset:2048
	ds_read_b128 v[182:185], v160 offset:3072
	ds_read_b128 v[186:189], v160 offset:4096
	ds_read_b128 v[196:199], v160 offset:5120
	ds_read_b128 v[200:203], v160 offset:6144
	ds_read_b128 v[204:207], v160 offset:7168
	global_load_lds_dwordx4 v[190:191], off
	s_add_i32 m0, s37, 0xe000
	v_lshl_add_u64 v[190:191], s[48:49], 0, v[138:139]
	global_load_lds_dwordx4 v[190:191], off
	s_waitcnt lgkmcnt(8)
	s_waitcnt lgkmcnt(0)
	s_barrier
	s_setprio 1
	v_mfma_f32_16x16x32_bf16 v[124:127], v[148:151], v[170:173], v[124:127]
	v_mfma_f32_16x16x32_bf16 v[120:123], v[162:165], v[170:173], v[120:123]
	v_mfma_f32_16x16x32_bf16 v[108:111], v[148:151], v[178:181], v[108:111]
	v_mfma_f32_16x16x32_bf16 v[104:107], v[162:165], v[178:181], v[104:107]
	v_mfma_f32_16x16x32_bf16 v[92:95], v[148:151], v[186:189], v[92:95]
	v_mfma_f32_16x16x32_bf16 v[88:91], v[162:165], v[186:189], v[88:91]
	v_mfma_f32_16x16x32_bf16 v[76:79], v[148:151], v[200:203], v[76:79]
	v_mfma_f32_16x16x32_bf16 v[72:75], v[162:165], v[200:203], v[72:75]
	v_mfma_f32_16x16x32_bf16 v[124:127], v[152:155], v[174:177], v[124:127]
	v_mfma_f32_16x16x32_bf16 v[120:123], v[166:169], v[174:177], v[120:123]
	v_mfma_f32_16x16x32_bf16 v[108:111], v[152:155], v[182:185], v[108:111]
	v_mfma_f32_16x16x32_bf16 v[104:107], v[166:169], v[182:185], v[104:107]
	v_mfma_f32_16x16x32_bf16 v[92:95], v[152:155], v[196:199], v[92:95]
	v_mfma_f32_16x16x32_bf16 v[88:91], v[166:169], v[196:199], v[88:91]
	v_mfma_f32_16x16x32_bf16 v[76:79], v[152:155], v[204:207], v[76:79]
	v_mfma_f32_16x16x32_bf16 v[72:75], v[166:169], v[204:207], v[72:75]
	s_setprio 0
	s_barrier
	s_add_i32 s64, s55, s23
	v_lshl_add_u64 v[190:191], s[50:51], 0, v[132:133]
	s_mov_b32 m0, s64
	ds_read_b128 v[208:211], v161
	ds_read_b128 v[212:215], v161 offset:1024
	ds_read_b128 v[216:219], v161 offset:2048
	ds_read_b128 v[220:223], v161 offset:3072
	global_load_lds_dwordx4 v[190:191], off
	s_add_i32 m0, s64, 0x2000
	v_lshl_add_u64 v[224:225], s[50:51], 0, v[128:129]
	global_load_lds_dwordx4 v[224:225], off
	s_waitcnt lgkmcnt(0)
	s_barrier
	s_setprio 1
	v_mfma_f32_16x16x32_bf16 v[116:119], v[208:211], v[170:173], v[116:119]
	v_mfma_f32_16x16x32_bf16 v[112:115], v[216:219], v[170:173], v[112:115]
	v_mfma_f32_16x16x32_bf16 v[100:103], v[208:211], v[178:181], v[100:103]
	v_mfma_f32_16x16x32_bf16 v[96:99], v[216:219], v[178:181], v[96:99]
	v_mfma_f32_16x16x32_bf16 v[84:87], v[208:211], v[186:189], v[84:87]
	v_mfma_f32_16x16x32_bf16 v[80:83], v[216:219], v[186:189], v[80:83]
	v_mfma_f32_16x16x32_bf16 v[68:71], v[208:211], v[200:203], v[68:71]
	v_mfma_f32_16x16x32_bf16 v[64:67], v[216:219], v[200:203], v[64:67]
	v_mfma_f32_16x16x32_bf16 v[116:119], v[212:215], v[174:177], v[116:119]
	v_mfma_f32_16x16x32_bf16 v[112:115], v[220:223], v[174:177], v[112:115]
	v_mfma_f32_16x16x32_bf16 v[100:103], v[212:215], v[182:185], v[100:103]
	v_mfma_f32_16x16x32_bf16 v[96:99], v[220:223], v[182:185], v[96:99]
	v_mfma_f32_16x16x32_bf16 v[84:87], v[212:215], v[196:199], v[84:87]
	v_mfma_f32_16x16x32_bf16 v[80:83], v[220:223], v[196:199], v[80:83]
	v_mfma_f32_16x16x32_bf16 v[68:71], v[212:215], v[204:207], v[68:71]
	v_mfma_f32_16x16x32_bf16 v[64:67], v[220:223], v[204:207], v[64:67]
	s_setprio 0
	s_mov_b32 m0, s37
	v_lshl_add_u64 v[226:227], s[20:21], 0, v[134:135]
	s_barrier
	ds_read_b128 v[170:173], v160 offset:16384
	ds_read_b128 v[174:177], v160 offset:17408
	ds_read_b128 v[178:181], v160 offset:18432
	ds_read_b128 v[182:185], v160 offset:19456
	ds_read_b128 v[186:189], v160 offset:20480
	ds_read_b128 v[196:199], v160 offset:21504
	ds_read_b128 v[200:203], v160 offset:22528
	ds_read_b128 v[204:207], v160 offset:23552
	global_load_lds_dwordx4 v[226:227], off
	s_mov_b32 m0, s38
	v_lshl_add_u64 v[228:229], s[20:21], 0, v[130:131]
	global_load_lds_dwordx4 v[228:229], off
	s_waitcnt lgkmcnt(0)
	s_barrier
	s_setprio 1
	v_mfma_f32_16x16x32_bf16 v[60:63], v[148:151], v[170:173], v[60:63]
	v_mfma_f32_16x16x32_bf16 v[56:59], v[162:165], v[170:173], v[56:59]
	v_mfma_f32_16x16x32_bf16 v[44:47], v[148:151], v[178:181], v[44:47]
	v_mfma_f32_16x16x32_bf16 v[40:43], v[162:165], v[178:181], v[40:43]
	v_mfma_f32_16x16x32_bf16 v[28:31], v[148:151], v[186:189], v[28:31]
	v_mfma_f32_16x16x32_bf16 v[24:27], v[162:165], v[186:189], v[24:27]
	v_mfma_f32_16x16x32_bf16 v[12:15], v[148:151], v[200:203], v[12:15]
	v_mfma_f32_16x16x32_bf16 v[8:11], v[162:165], v[200:203], v[8:11]
	v_mfma_f32_16x16x32_bf16 v[60:63], v[152:155], v[174:177], v[60:63]
	v_mfma_f32_16x16x32_bf16 v[56:59], v[166:169], v[174:177], v[56:59]
	v_mfma_f32_16x16x32_bf16 v[44:47], v[152:155], v[182:185], v[44:47]
	v_mfma_f32_16x16x32_bf16 v[40:43], v[166:169], v[182:185], v[40:43]
	v_mfma_f32_16x16x32_bf16 v[28:31], v[152:155], v[196:199], v[28:31]
	v_mfma_f32_16x16x32_bf16 v[24:27], v[166:169], v[196:199], v[24:27]
	v_mfma_f32_16x16x32_bf16 v[12:15], v[152:155], v[204:207], v[12:15]
	v_mfma_f32_16x16x32_bf16 v[8:11], v[166:169], v[204:207], v[8:11]
	s_setprio 0
	s_barrier
	s_add_u32 s64, s50, 0x200000
	s_addc_u32 s65, s51, 0
	s_add_i32 s66, s57, s23
	s_mov_b32 m0, s66
	v_lshl_add_u64 v[148:149], s[64:65], 0, v[132:133]
	global_load_lds_dwordx4 v[148:149], off
	s_add_i32 m0, s66, 0x2000
	v_lshl_add_u64 v[148:149], s[64:65], 0, v[128:129]
	global_load_lds_dwordx4 v[148:149], off
	s_waitcnt vmcnt(6)
	s_barrier
	s_setprio 1
	v_mfma_f32_16x16x32_bf16 v[52:55], v[208:211], v[170:173], v[52:55]
	v_mfma_f32_16x16x32_bf16 v[48:51], v[216:219], v[170:173], v[48:51]
	v_mfma_f32_16x16x32_bf16 v[36:39], v[208:211], v[178:181], v[36:39]
	v_mfma_f32_16x16x32_bf16 v[32:35], v[216:219], v[178:181], v[32:35]
	v_mfma_f32_16x16x32_bf16 v[20:23], v[208:211], v[186:189], v[20:23]
	v_mfma_f32_16x16x32_bf16 v[16:19], v[216:219], v[186:189], v[16:19]
	v_mfma_f32_16x16x32_bf16 v[4:7], v[208:211], v[200:203], v[4:7]
	v_mfma_f32_16x16x32_bf16 v[0:3], v[216:219], v[200:203], v[0:3]
	v_mfma_f32_16x16x32_bf16 v[52:55], v[212:215], v[174:177], v[52:55]
	v_mfma_f32_16x16x32_bf16 v[48:51], v[220:223], v[174:177], v[48:51]
	v_mfma_f32_16x16x32_bf16 v[36:39], v[212:215], v[182:185], v[36:39]
	v_mfma_f32_16x16x32_bf16 v[32:35], v[220:223], v[182:185], v[32:35]
	v_mfma_f32_16x16x32_bf16 v[20:23], v[212:215], v[196:199], v[20:23]
	v_mfma_f32_16x16x32_bf16 v[16:19], v[220:223], v[196:199], v[16:19]
	v_mfma_f32_16x16x32_bf16 v[4:7], v[212:215], v[204:207], v[4:7]
	v_mfma_f32_16x16x32_bf16 v[0:3], v[220:223], v[204:207], v[0:3]
	s_setprio 0
	s_add_i32 s64, 0, 0x18000
	v_add_u32_e32 v166, s64, v156
	s_barrier
	ds_read_b128 v[148:151], v166
	ds_read_b128 v[152:155], v166 offset:1024
	ds_read_b128 v[162:165], v166 offset:2048
	ds_read_b128 v[166:169], v166 offset:3072
	s_add_u32 s20, s20, 0x200000
	s_addc_u32 s21, s21, 0
	s_mov_b32 m0, s39
	v_lshl_add_u64 v[208:209], s[20:21], 0, v[134:135]
	ds_read_b128 v[170:173], v160 offset:32768
	ds_read_b128 v[174:177], v160 offset:33792
	ds_read_b128 v[178:181], v160 offset:34816
	ds_read_b128 v[182:185], v160 offset:35840
	ds_read_b128 v[186:189], v160 offset:36864
	ds_read_b128 v[196:199], v160 offset:37888
	ds_read_b128 v[200:203], v160 offset:38912
	ds_read_b128 v[204:207], v160 offset:39936
	global_load_lds_dwordx4 v[208:209], off
	s_mov_b32 m0, s47
	v_lshl_add_u64 v[208:209], s[20:21], 0, v[130:131]
	global_load_lds_dwordx4 v[208:209], off
	s_waitcnt lgkmcnt(8)
	s_waitcnt lgkmcnt(0)
	s_barrier
	s_setprio 1
	v_mfma_f32_16x16x32_bf16 v[124:127], v[148:151], v[170:173], v[124:127]
	v_mfma_f32_16x16x32_bf16 v[120:123], v[162:165], v[170:173], v[120:123]
	v_mfma_f32_16x16x32_bf16 v[108:111], v[148:151], v[178:181], v[108:111]
	v_mfma_f32_16x16x32_bf16 v[104:107], v[162:165], v[178:181], v[104:107]
	v_mfma_f32_16x16x32_bf16 v[92:95], v[148:151], v[186:189], v[92:95]
	v_mfma_f32_16x16x32_bf16 v[88:91], v[162:165], v[186:189], v[88:91]
	v_mfma_f32_16x16x32_bf16 v[76:79], v[148:151], v[200:203], v[76:79]
	v_mfma_f32_16x16x32_bf16 v[72:75], v[162:165], v[200:203], v[72:75]
	v_mfma_f32_16x16x32_bf16 v[124:127], v[152:155], v[174:177], v[124:127]
	v_mfma_f32_16x16x32_bf16 v[120:123], v[166:169], v[174:177], v[120:123]
	v_mfma_f32_16x16x32_bf16 v[108:111], v[152:155], v[182:185], v[108:111]
	v_mfma_f32_16x16x32_bf16 v[104:107], v[166:169], v[182:185], v[104:107]
	v_mfma_f32_16x16x32_bf16 v[92:95], v[152:155], v[196:199], v[92:95]
	v_mfma_f32_16x16x32_bf16 v[88:91], v[166:169], v[196:199], v[88:91]
	v_mfma_f32_16x16x32_bf16 v[76:79], v[152:155], v[204:207], v[76:79]
	v_mfma_f32_16x16x32_bf16 v[72:75], v[166:169], v[204:207], v[72:75]
	s_setprio 0
	s_barrier
	s_add_i32 s65, 0, 0x1c000
	s_add_i32 s20, s64, s23
	v_add_u32_e32 v195, s65, v156
	v_lshl_add_u64 v[190:191], v[190:191], 0, s[10:11]
	s_mov_b32 m0, s20
	ds_read_b128 v[208:211], v195
	ds_read_b128 v[212:215], v195 offset:1024
	ds_read_b128 v[216:219], v195 offset:2048
	ds_read_b128 v[220:223], v195 offset:3072
	global_load_lds_dwordx4 v[190:191], off
	s_add_i32 m0, s20, 0x2000
	v_lshl_add_u64 v[190:191], v[224:225], 0, s[10:11]
	global_load_lds_dwordx4 v[190:191], off
	s_waitcnt lgkmcnt(0)
	s_barrier
	s_setprio 1
	v_mfma_f32_16x16x32_bf16 v[116:119], v[208:211], v[170:173], v[116:119]
	v_mfma_f32_16x16x32_bf16 v[112:115], v[216:219], v[170:173], v[112:115]
	v_mfma_f32_16x16x32_bf16 v[100:103], v[208:211], v[178:181], v[100:103]
	v_mfma_f32_16x16x32_bf16 v[96:99], v[216:219], v[178:181], v[96:99]
	v_mfma_f32_16x16x32_bf16 v[84:87], v[208:211], v[186:189], v[84:87]
	v_mfma_f32_16x16x32_bf16 v[80:83], v[216:219], v[186:189], v[80:83]
	v_mfma_f32_16x16x32_bf16 v[68:71], v[208:211], v[200:203], v[68:71]
	v_mfma_f32_16x16x32_bf16 v[64:67], v[216:219], v[200:203], v[64:67]
	v_mfma_f32_16x16x32_bf16 v[116:119], v[212:215], v[174:177], v[116:119]
	v_mfma_f32_16x16x32_bf16 v[112:115], v[220:223], v[174:177], v[112:115]
	v_mfma_f32_16x16x32_bf16 v[100:103], v[212:215], v[182:185], v[100:103]
	v_mfma_f32_16x16x32_bf16 v[96:99], v[220:223], v[182:185], v[96:99]
	v_mfma_f32_16x16x32_bf16 v[84:87], v[212:215], v[196:199], v[84:87]
	v_mfma_f32_16x16x32_bf16 v[80:83], v[220:223], v[196:199], v[80:83]
	v_mfma_f32_16x16x32_bf16 v[68:71], v[212:215], v[204:207], v[68:71]
	v_mfma_f32_16x16x32_bf16 v[64:67], v[220:223], v[204:207], v[64:67]
	s_setprio 0
	s_mov_b32 m0, s34
	v_lshl_add_u64 v[190:191], v[226:227], 0, s[10:11]
	s_barrier
	ds_read_b128 v[170:173], v160 offset:49152
	ds_read_b128 v[174:177], v160 offset:50176
	ds_read_b128 v[178:181], v160 offset:51200
	ds_read_b128 v[182:185], v160 offset:52224
	ds_read_b128 v[186:189], v160 offset:53248
	ds_read_b128 v[196:199], v160 offset:54272
	ds_read_b128 v[200:203], v160 offset:55296
	ds_read_b128 v[204:207], v160 offset:56320
	global_load_lds_dwordx4 v[190:191], off
	s_mov_b32 m0, s35
	v_lshl_add_u64 v[190:191], v[228:229], 0, s[10:11]
	global_load_lds_dwordx4 v[190:191], off
	s_waitcnt lgkmcnt(0)
	s_barrier
	s_setprio 1
	v_mfma_f32_16x16x32_bf16 v[60:63], v[148:151], v[170:173], v[60:63]
	v_mfma_f32_16x16x32_bf16 v[56:59], v[162:165], v[170:173], v[56:59]
	v_mfma_f32_16x16x32_bf16 v[44:47], v[148:151], v[178:181], v[44:47]
	v_mfma_f32_16x16x32_bf16 v[40:43], v[162:165], v[178:181], v[40:43]
	v_mfma_f32_16x16x32_bf16 v[28:31], v[148:151], v[186:189], v[28:31]
	v_mfma_f32_16x16x32_bf16 v[24:27], v[162:165], v[186:189], v[24:27]
	v_mfma_f32_16x16x32_bf16 v[12:15], v[148:151], v[200:203], v[12:15]
	v_mfma_f32_16x16x32_bf16 v[8:11], v[162:165], v[200:203], v[8:11]
	v_mfma_f32_16x16x32_bf16 v[60:63], v[152:155], v[174:177], v[60:63]
	v_mfma_f32_16x16x32_bf16 v[56:59], v[166:169], v[174:177], v[56:59]
	v_mfma_f32_16x16x32_bf16 v[44:47], v[152:155], v[182:185], v[44:47]
	v_mfma_f32_16x16x32_bf16 v[40:43], v[166:169], v[182:185], v[40:43]
	v_mfma_f32_16x16x32_bf16 v[28:31], v[152:155], v[196:199], v[28:31]
	v_mfma_f32_16x16x32_bf16 v[24:27], v[166:169], v[196:199], v[24:27]
	v_mfma_f32_16x16x32_bf16 v[12:15], v[152:155], v[204:207], v[12:15]
	v_mfma_f32_16x16x32_bf16 v[8:11], v[166:169], v[204:207], v[8:11]
	s_setprio 0
	s_barrier
	s_add_u32 s20, s50, 0x200080
	s_addc_u32 s21, s51, 0
	s_add_i32 s50, s65, s23
	s_mov_b32 m0, s50
	v_lshl_add_u64 v[148:149], s[20:21], 0, v[132:133]
	global_load_lds_dwordx4 v[148:149], off
	s_add_i32 m0, s50, 0x2000
	v_lshl_add_u64 v[148:149], s[20:21], 0, v[128:129]
	global_load_lds_dwordx4 v[148:149], off
	s_waitcnt vmcnt(6)
	s_barrier
	s_setprio 1
	v_mfma_f32_16x16x32_bf16 v[52:55], v[208:211], v[170:173], v[52:55]
	v_mfma_f32_16x16x32_bf16 v[48:51], v[216:219], v[170:173], v[48:51]
	v_mfma_f32_16x16x32_bf16 v[36:39], v[208:211], v[178:181], v[36:39]
	v_mfma_f32_16x16x32_bf16 v[32:35], v[216:219], v[178:181], v[32:35]
	v_mfma_f32_16x16x32_bf16 v[20:23], v[208:211], v[186:189], v[20:23]
	v_mfma_f32_16x16x32_bf16 v[16:19], v[216:219], v[186:189], v[16:19]
	v_mfma_f32_16x16x32_bf16 v[4:7], v[208:211], v[200:203], v[4:7]
	v_mfma_f32_16x16x32_bf16 v[0:3], v[216:219], v[200:203], v[0:3]
	v_mfma_f32_16x16x32_bf16 v[52:55], v[212:215], v[174:177], v[52:55]
	v_mfma_f32_16x16x32_bf16 v[48:51], v[220:223], v[174:177], v[48:51]
	v_mfma_f32_16x16x32_bf16 v[36:39], v[212:215], v[182:185], v[36:39]
	v_mfma_f32_16x16x32_bf16 v[32:35], v[220:223], v[182:185], v[32:35]
	v_mfma_f32_16x16x32_bf16 v[20:23], v[212:215], v[196:199], v[20:23]
	v_mfma_f32_16x16x32_bf16 v[16:19], v[220:223], v[196:199], v[16:19]
	v_mfma_f32_16x16x32_bf16 v[4:7], v[212:215], v[204:207], v[4:7]
	v_mfma_f32_16x16x32_bf16 v[0:3], v[220:223], v[204:207], v[0:3]
	s_setprio 0
	s_add_i32 s63, s63, 2
	s_add_u32 s48, s48, 0x100
	s_addc_u32 s49, s49, 0
	s_add_u32 s61, s61, 0x100
	s_addc_u32 s62, s62, 0
	s_cmpk_gt_u32 s63, 0x7d
	s_cbranch_scc1 .Lepi_last_mlpout0
	s_barrier
	s_branch .LBB0_1030

.LBB0_1090:
	ds_read_b128 v[148:151], v163
	ds_read_b128 v[166:169], v163 offset:1024
	ds_read_b128 v[170:173], v163 offset:2048
	ds_read_b128 v[174:177], v163 offset:3072
	s_add_u32 s18, s16, 0xfff80080
	s_addc_u32 s19, s17, -1
	s_cmp_eq_u32 s35, 28
	s_cselect_b32 s21, s1, s19
	s_cselect_b32 s20, s15, s18
	s_cselect_b32 s19, s22, s34
	s_cselect_b32 s18, s23, s33
	v_lshl_add_u64 v[142:143], s[16:17], 0, v[134:135]
	s_add_i32 m0, s38, 0xc000
	ds_read_b128 v[178:181], v164
	ds_read_b128 v[182:185], v164 offset:1024
	ds_read_b128 v[186:189], v164 offset:2048
	ds_read_b128 v[196:199], v164 offset:3072
	ds_read_b128 v[200:203], v164 offset:4096
	ds_read_b128 v[204:207], v164 offset:5120
	ds_read_b128 v[208:211], v164 offset:6144
	ds_read_b128 v[212:215], v164 offset:7168
	global_load_lds_dwordx4 v[142:143], off
	s_add_i32 m0, s38, 0xe000
	v_lshl_add_u64 v[142:143], s[16:17], 0, v[136:137]
	global_load_lds_dwordx4 v[142:143], off
	s_waitcnt lgkmcnt(8)
	s_waitcnt lgkmcnt(0)
	s_barrier
	s_setprio 1
	v_mfma_f32_16x16x32_bf16 v[124:127], v[148:151], v[178:181], v[124:127]
	v_mfma_f32_16x16x32_bf16 v[120:123], v[170:173], v[178:181], v[120:123]
	v_mfma_f32_16x16x32_bf16 v[108:111], v[148:151], v[186:189], v[108:111]
	v_mfma_f32_16x16x32_bf16 v[104:107], v[170:173], v[186:189], v[104:107]
	v_mfma_f32_16x16x32_bf16 v[92:95], v[148:151], v[200:203], v[92:95]
	v_mfma_f32_16x16x32_bf16 v[88:91], v[170:173], v[200:203], v[88:91]
	v_mfma_f32_16x16x32_bf16 v[76:79], v[148:151], v[208:211], v[76:79]
	v_mfma_f32_16x16x32_bf16 v[72:75], v[170:173], v[208:211], v[72:75]
	v_mfma_f32_16x16x32_bf16 v[124:127], v[166:169], v[182:185], v[124:127]
	v_mfma_f32_16x16x32_bf16 v[120:123], v[174:177], v[182:185], v[120:123]
	v_mfma_f32_16x16x32_bf16 v[108:111], v[166:169], v[196:199], v[108:111]
	v_mfma_f32_16x16x32_bf16 v[104:107], v[174:177], v[196:199], v[104:107]
	v_mfma_f32_16x16x32_bf16 v[92:95], v[166:169], v[204:207], v[92:95]
	v_mfma_f32_16x16x32_bf16 v[88:91], v[174:177], v[204:207], v[88:91]
	v_mfma_f32_16x16x32_bf16 v[76:79], v[166:169], v[212:215], v[76:79]
	v_mfma_f32_16x16x32_bf16 v[72:75], v[174:177], v[212:215], v[72:75]
	s_setprio 0
	s_barrier
	s_add_i32 s49, s65, s37
	v_lshl_add_u64 v[142:143], s[18:19], 0, v[128:129]
	s_mov_b32 m0, s49
	ds_read_b128 v[216:219], v165
	ds_read_b128 v[220:223], v165 offset:1024
	ds_read_b128 v[224:227], v165 offset:2048
	ds_read_b128 v[228:231], v165 offset:3072
	global_load_lds_dwordx4 v[142:143], off
	s_add_i32 m0, s49, 0x2000
	v_lshl_add_u64 v[152:153], s[18:19], 0, v[130:131]
	global_load_lds_dwordx4 v[152:153], off
	s_waitcnt lgkmcnt(0)
	s_barrier
	s_setprio 1
	v_mfma_f32_16x16x32_bf16 v[116:119], v[216:219], v[178:181], v[116:119]
	v_mfma_f32_16x16x32_bf16 v[112:115], v[224:227], v[178:181], v[112:115]
	v_mfma_f32_16x16x32_bf16 v[100:103], v[216:219], v[186:189], v[100:103]
	v_mfma_f32_16x16x32_bf16 v[96:99], v[224:227], v[186:189], v[96:99]
	v_mfma_f32_16x16x32_bf16 v[84:87], v[216:219], v[200:203], v[84:87]
	v_mfma_f32_16x16x32_bf16 v[80:83], v[224:227], v[200:203], v[80:83]
	v_mfma_f32_16x16x32_bf16 v[68:71], v[216:219], v[208:211], v[68:71]
	v_mfma_f32_16x16x32_bf16 v[64:67], v[224:227], v[208:211], v[64:67]
	v_mfma_f32_16x16x32_bf16 v[116:119], v[220:223], v[182:185], v[116:119]
	v_mfma_f32_16x16x32_bf16 v[112:115], v[228:231], v[182:185], v[112:115]
	v_mfma_f32_16x16x32_bf16 v[100:103], v[220:223], v[196:199], v[100:103]
	v_mfma_f32_16x16x32_bf16 v[96:99], v[228:231], v[196:199], v[96:99]
	v_mfma_f32_16x16x32_bf16 v[84:87], v[220:223], v[204:207], v[84:87]
	v_mfma_f32_16x16x32_bf16 v[80:83], v[228:231], v[204:207], v[80:83]
	v_mfma_f32_16x16x32_bf16 v[68:71], v[220:223], v[212:215], v[68:71]
	v_mfma_f32_16x16x32_bf16 v[64:67], v[228:231], v[212:215], v[64:67]
	s_setprio 0
	s_mov_b32 m0, s38
	v_lshl_add_u64 v[190:191], s[20:21], 0, v[128:129]
	s_barrier
	ds_read_b128 v[178:181], v164 offset:16384
	ds_read_b128 v[182:185], v164 offset:17408
	ds_read_b128 v[186:189], v164 offset:18432
	ds_read_b128 v[196:199], v164 offset:19456
	ds_read_b128 v[200:203], v164 offset:20480
	ds_read_b128 v[204:207], v164 offset:21504
	ds_read_b128 v[208:211], v164 offset:22528
	ds_read_b128 v[212:215], v164 offset:23552
	global_load_lds_dwordx4 v[190:191], off
	s_mov_b32 m0, s39
	v_lshl_add_u64 v[232:233], s[20:21], 0, v[130:131]
	global_load_lds_dwordx4 v[232:233], off
	s_waitcnt lgkmcnt(0)
	s_barrier
	s_setprio 1
	v_mfma_f32_16x16x32_bf16 v[60:63], v[148:151], v[178:181], v[60:63]
	v_mfma_f32_16x16x32_bf16 v[56:59], v[170:173], v[178:181], v[56:59]
	v_mfma_f32_16x16x32_bf16 v[44:47], v[148:151], v[186:189], v[44:47]
	v_mfma_f32_16x16x32_bf16 v[40:43], v[170:173], v[186:189], v[40:43]
	v_mfma_f32_16x16x32_bf16 v[28:31], v[148:151], v[200:203], v[28:31]
	v_mfma_f32_16x16x32_bf16 v[24:27], v[170:173], v[200:203], v[24:27]
	v_mfma_f32_16x16x32_bf16 v[12:15], v[148:151], v[208:211], v[12:15]
	v_mfma_f32_16x16x32_bf16 v[8:11], v[170:173], v[208:211], v[8:11]
	v_mfma_f32_16x16x32_bf16 v[60:63], v[166:169], v[182:185], v[60:63]
	v_mfma_f32_16x16x32_bf16 v[56:59], v[174:177], v[182:185], v[56:59]
	v_mfma_f32_16x16x32_bf16 v[44:47], v[166:169], v[196:199], v[44:47]
	v_mfma_f32_16x16x32_bf16 v[40:43], v[174:177], v[196:199], v[40:43]
	v_mfma_f32_16x16x32_bf16 v[28:31], v[166:169], v[204:207], v[28:31]
	v_mfma_f32_16x16x32_bf16 v[24:27], v[174:177], v[204:207], v[24:27]
	v_mfma_f32_16x16x32_bf16 v[12:15], v[166:169], v[212:215], v[12:15]
	v_mfma_f32_16x16x32_bf16 v[8:11], v[174:177], v[212:215], v[8:11]
	s_setprio 0
	s_barrier
	s_add_u32 s80, s18, 0x80000
	s_addc_u32 s81, s19, 0
	s_add_i32 s49, s67, s37
	s_mov_b32 m0, s49
	v_lshl_add_u64 v[148:149], s[80:81], 0, v[128:129]
	global_load_lds_dwordx4 v[148:149], off
	s_add_i32 m0, s49, 0x2000
	v_lshl_add_u64 v[148:149], s[80:81], 0, v[130:131]
	global_load_lds_dwordx4 v[148:149], off
	s_waitcnt vmcnt(6)
	s_barrier
	s_setprio 1
	v_mfma_f32_16x16x32_bf16 v[52:55], v[216:219], v[178:181], v[52:55]
	v_mfma_f32_16x16x32_bf16 v[48:51], v[224:227], v[178:181], v[48:51]
	v_mfma_f32_16x16x32_bf16 v[36:39], v[216:219], v[186:189], v[36:39]
	v_mfma_f32_16x16x32_bf16 v[32:35], v[224:227], v[186:189], v[32:35]
	v_mfma_f32_16x16x32_bf16 v[20:23], v[216:219], v[200:203], v[20:23]
	v_mfma_f32_16x16x32_bf16 v[16:19], v[224:227], v[200:203], v[16:19]
	v_mfma_f32_16x16x32_bf16 v[4:7], v[216:219], v[208:211], v[4:7]
	v_mfma_f32_16x16x32_bf16 v[0:3], v[224:227], v[208:211], v[0:3]
	v_mfma_f32_16x16x32_bf16 v[52:55], v[220:223], v[182:185], v[52:55]
	v_mfma_f32_16x16x32_bf16 v[48:51], v[228:231], v[182:185], v[48:51]
	v_mfma_f32_16x16x32_bf16 v[36:39], v[220:223], v[196:199], v[36:39]
	v_mfma_f32_16x16x32_bf16 v[32:35], v[228:231], v[196:199], v[32:35]
	v_mfma_f32_16x16x32_bf16 v[20:23], v[220:223], v[204:207], v[20:23]
	v_mfma_f32_16x16x32_bf16 v[16:19], v[228:231], v[204:207], v[16:19]
	v_mfma_f32_16x16x32_bf16 v[4:7], v[220:223], v[212:215], v[4:7]
	v_mfma_f32_16x16x32_bf16 v[0:3], v[228:231], v[212:215], v[0:3]
	s_setprio 0
	s_add_i32 s49, 0, 0x18000
	v_add_u32_e32 v132, s49, v154
	s_barrier
	ds_read_b128 v[148:151], v132
	ds_read_b128 v[166:169], v132 offset:1024
	ds_read_b128 v[170:173], v132 offset:2048
	ds_read_b128 v[174:177], v132 offset:3072
	s_add_u32 s20, s20, 0x80000
	s_addc_u32 s21, s21, 0
	s_mov_b32 m0, s56
	v_lshl_add_u64 v[216:217], s[20:21], 0, v[128:129]
	ds_read_b128 v[178:181], v164 offset:32768
	ds_read_b128 v[182:185], v164 offset:33792
	ds_read_b128 v[186:189], v164 offset:34816
	ds_read_b128 v[196:199], v164 offset:35840
	ds_read_b128 v[200:203], v164 offset:36864
	ds_read_b128 v[204:207], v164 offset:37888
	ds_read_b128 v[208:211], v164 offset:38912
	ds_read_b128 v[212:215], v164 offset:39936
	global_load_lds_dwordx4 v[216:217], off
	s_mov_b32 m0, s57
	v_lshl_add_u64 v[216:217], s[20:21], 0, v[130:131]
	global_load_lds_dwordx4 v[216:217], off
	s_waitcnt lgkmcnt(8)
	s_waitcnt lgkmcnt(0)
	s_barrier
	s_setprio 1
	v_mfma_f32_16x16x32_bf16 v[124:127], v[148:151], v[178:181], v[124:127]
	v_mfma_f32_16x16x32_bf16 v[120:123], v[170:173], v[178:181], v[120:123]
	v_mfma_f32_16x16x32_bf16 v[108:111], v[148:151], v[186:189], v[108:111]
	v_mfma_f32_16x16x32_bf16 v[104:107], v[170:173], v[186:189], v[104:107]
	v_mfma_f32_16x16x32_bf16 v[92:95], v[148:151], v[200:203], v[92:95]
	v_mfma_f32_16x16x32_bf16 v[88:91], v[170:173], v[200:203], v[88:91]
	v_mfma_f32_16x16x32_bf16 v[76:79], v[148:151], v[208:211], v[76:79]
	v_mfma_f32_16x16x32_bf16 v[72:75], v[170:173], v[208:211], v[72:75]
	v_mfma_f32_16x16x32_bf16 v[124:127], v[166:169], v[182:185], v[124:127]
	v_mfma_f32_16x16x32_bf16 v[120:123], v[174:177], v[182:185], v[120:123]
	v_mfma_f32_16x16x32_bf16 v[108:111], v[166:169], v[196:199], v[108:111]
	v_mfma_f32_16x16x32_bf16 v[104:107], v[174:177], v[196:199], v[104:107]
	v_mfma_f32_16x16x32_bf16 v[92:95], v[166:169], v[204:207], v[92:95]
	v_mfma_f32_16x16x32_bf16 v[88:91], v[174:177], v[204:207], v[88:91]
	v_mfma_f32_16x16x32_bf16 v[76:79], v[166:169], v[212:215], v[76:79]
	v_mfma_f32_16x16x32_bf16 v[72:75], v[174:177], v[212:215], v[72:75]
	s_setprio 0
	s_barrier
	s_add_i32 s20, 0, 0x1c000
	s_add_i32 s21, s49, s37
	v_add_u32_e32 v132, s20, v154
	v_lshl_add_u64 v[142:143], v[142:143], 0, s[46:47]
	s_mov_b32 m0, s21
	ds_read_b128 v[216:219], v132
	ds_read_b128 v[220:223], v132 offset:1024
	ds_read_b128 v[224:227], v132 offset:2048
	ds_read_b128 v[228:231], v132 offset:3072
	global_load_lds_dwordx4 v[142:143], off
	s_add_i32 m0, s21, 0x2000
	v_lshl_add_u64 v[142:143], v[152:153], 0, s[46:47]
	global_load_lds_dwordx4 v[142:143], off
	s_waitcnt lgkmcnt(0)
	s_barrier
	s_setprio 1
	v_mfma_f32_16x16x32_bf16 v[116:119], v[216:219], v[178:181], v[116:119]
	v_mfma_f32_16x16x32_bf16 v[112:115], v[224:227], v[178:181], v[112:115]
	v_mfma_f32_16x16x32_bf16 v[100:103], v[216:219], v[186:189], v[100:103]
	v_mfma_f32_16x16x32_bf16 v[96:99], v[224:227], v[186:189], v[96:99]
	v_mfma_f32_16x16x32_bf16 v[84:87], v[216:219], v[200:203], v[84:87]
	v_mfma_f32_16x16x32_bf16 v[80:83], v[224:227], v[200:203], v[80:83]
	v_mfma_f32_16x16x32_bf16 v[68:71], v[216:219], v[208:211], v[68:71]
	v_mfma_f32_16x16x32_bf16 v[64:67], v[224:227], v[208:211], v[64:67]
	v_mfma_f32_16x16x32_bf16 v[116:119], v[220:223], v[182:185], v[116:119]
	v_mfma_f32_16x16x32_bf16 v[112:115], v[228:231], v[182:185], v[112:115]
	v_mfma_f32_16x16x32_bf16 v[100:103], v[220:223], v[196:199], v[100:103]
	v_mfma_f32_16x16x32_bf16 v[96:99], v[228:231], v[196:199], v[96:99]
	v_mfma_f32_16x16x32_bf16 v[84:87], v[220:223], v[204:207], v[84:87]
	v_mfma_f32_16x16x32_bf16 v[80:83], v[228:231], v[204:207], v[80:83]
	v_mfma_f32_16x16x32_bf16 v[68:71], v[220:223], v[212:215], v[68:71]
	v_mfma_f32_16x16x32_bf16 v[64:67], v[228:231], v[212:215], v[64:67]
	s_setprio 0
	s_mov_b32 m0, s60
	v_lshl_add_u64 v[142:143], v[190:191], 0, s[46:47]
	s_barrier
	ds_read_b128 v[178:181], v164 offset:49152
	ds_read_b128 v[182:185], v164 offset:50176
	ds_read_b128 v[186:189], v164 offset:51200
	ds_read_b128 v[196:199], v164 offset:52224
	ds_read_b128 v[200:203], v164 offset:53248
	ds_read_b128 v[204:207], v164 offset:54272
	ds_read_b128 v[208:211], v164 offset:55296
	ds_read_b128 v[212:215], v164 offset:56320
	global_load_lds_dwordx4 v[142:143], off
	s_mov_b32 m0, s61
	v_lshl_add_u64 v[142:143], v[232:233], 0, s[46:47]
	global_load_lds_dwordx4 v[142:143], off
	s_waitcnt lgkmcnt(0)
	s_barrier
	s_setprio 1
	v_mfma_f32_16x16x32_bf16 v[60:63], v[148:151], v[178:181], v[60:63]
	v_mfma_f32_16x16x32_bf16 v[56:59], v[170:173], v[178:181], v[56:59]
	v_mfma_f32_16x16x32_bf16 v[44:47], v[148:151], v[186:189], v[44:47]
	v_mfma_f32_16x16x32_bf16 v[40:43], v[170:173], v[186:189], v[40:43]
	v_mfma_f32_16x16x32_bf16 v[28:31], v[148:151], v[200:203], v[28:31]
	v_mfma_f32_16x16x32_bf16 v[24:27], v[170:173], v[200:203], v[24:27]
	v_mfma_f32_16x16x32_bf16 v[12:15], v[148:151], v[208:211], v[12:15]
	v_mfma_f32_16x16x32_bf16 v[8:11], v[170:173], v[208:211], v[8:11]
	v_mfma_f32_16x16x32_bf16 v[60:63], v[166:169], v[182:185], v[60:63]
	v_mfma_f32_16x16x32_bf16 v[56:59], v[174:177], v[182:185], v[56:59]
	v_mfma_f32_16x16x32_bf16 v[44:47], v[166:169], v[196:199], v[44:47]
	v_mfma_f32_16x16x32_bf16 v[40:43], v[174:177], v[196:199], v[40:43]
	v_mfma_f32_16x16x32_bf16 v[28:31], v[166:169], v[204:207], v[28:31]
	v_mfma_f32_16x16x32_bf16 v[24:27], v[174:177], v[204:207], v[24:27]
	v_mfma_f32_16x16x32_bf16 v[12:15], v[166:169], v[212:215], v[12:15]
	v_mfma_f32_16x16x32_bf16 v[8:11], v[174:177], v[212:215], v[8:11]
	s_setprio 0
	s_barrier
	s_add_u32 s18, s18, 0x80080
	s_addc_u32 s19, s19, 0
	s_add_i32 s20, s20, s37
	s_mov_b32 m0, s20
	v_lshl_add_u64 v[142:143], s[18:19], 0, v[128:129]
	global_load_lds_dwordx4 v[142:143], off
	s_add_i32 m0, s20, 0x2000
	v_lshl_add_u64 v[142:143], s[18:19], 0, v[130:131]
	global_load_lds_dwordx4 v[142:143], off
	s_waitcnt vmcnt(6)
	s_barrier
	s_setprio 1
	v_mfma_f32_16x16x32_bf16 v[52:55], v[216:219], v[178:181], v[52:55]
	v_mfma_f32_16x16x32_bf16 v[48:51], v[224:227], v[178:181], v[48:51]
	v_mfma_f32_16x16x32_bf16 v[36:39], v[216:219], v[186:189], v[36:39]
	v_mfma_f32_16x16x32_bf16 v[32:35], v[224:227], v[186:189], v[32:35]
	v_mfma_f32_16x16x32_bf16 v[20:23], v[216:219], v[200:203], v[20:23]
	v_mfma_f32_16x16x32_bf16 v[16:19], v[224:227], v[200:203], v[16:19]
	v_mfma_f32_16x16x32_bf16 v[4:7], v[216:219], v[208:211], v[4:7]
	v_mfma_f32_16x16x32_bf16 v[0:3], v[224:227], v[208:211], v[0:3]
	v_mfma_f32_16x16x32_bf16 v[52:55], v[220:223], v[182:185], v[52:55]
	v_mfma_f32_16x16x32_bf16 v[48:51], v[228:231], v[182:185], v[48:51]
	v_mfma_f32_16x16x32_bf16 v[36:39], v[220:223], v[196:199], v[36:39]
	v_mfma_f32_16x16x32_bf16 v[32:35], v[228:231], v[196:199], v[32:35]
	v_mfma_f32_16x16x32_bf16 v[20:23], v[220:223], v[204:207], v[20:23]
	v_mfma_f32_16x16x32_bf16 v[16:19], v[228:231], v[204:207], v[16:19]
	v_mfma_f32_16x16x32_bf16 v[4:7], v[220:223], v[212:215], v[4:7]
	v_mfma_f32_16x16x32_bf16 v[0:3], v[228:231], v[212:215], v[0:3]
	s_setprio 0
	s_add_i32 s35, s35, 2
	s_add_u32 s16, s16, 0x100
	s_addc_u32 s17, s17, 0
	s_add_u32 s33, s33, 0x100
	s_addc_u32 s34, s34, 0
	s_cmp_gt_u32 s35, 29
	s_barrier
	s_cbranch_scc0 .LBB0_1090
	s_lshl_b32 s34, s14, 8
	s_add_i32 s34, s34, s59
	v_or_b32_e32 v150, s34, v147
	v_lshl_or_b32 v142, s0, 8, v162
	v_ashrrev_i32_e32 v151, 31, v150
	v_cmp_gt_i32_e64 s[18:19], s58, v150
	v_cmp_lt_i32_e64 s[16:17], s68, v150
	v_lshlrev_b64 v[148:149], 8, v[150:151]
	v_cmp_lt_i32_e64 s[14:15], s76, v142
	v_add_u32_e32 v132, 0xfffff700, v142
	v_add_u32_e32 v174, 0xfffff710, v142
	v_add_u32_e32 v172, 0xfffff701, v142
	v_add_u32_e32 v170, 0xfffff711, v142
	v_add_u32_e32 v169, 0xfffff702, v142
	v_add_u32_e32 v168, 0xfffff712, v142
	v_add_u32_e32 v167, 0xfffff703, v142
	v_add_u32_e32 v166, 0xfffff713, v142
	v_lshl_add_u64 v[152:153], v[150:151], 1, s[24:25]
	s_and_saveexec_b64 s[0:1], s[14:15]
	s_xor_b64 s[0:1], exec, s[0:1]
	s_cbranch_execz .LBB0_1095
	v_bfe_u32 v143, v124, 16, 1
	v_add3_u32 v143, v124, v143, s77
	v_mad_u64_u32 v[176:177], s[20:21], v132, s66, v[152:153]
	global_store_short_d16_hi v[176:177], v143, off
	v_bfe_u32 v143, v120, 16, 1
	v_add3_u32 v143, v120, v143, s77
	v_mad_u64_u32 v[176:177], s[20:21], v174, s66, v[152:153]
	global_store_short_d16_hi v[176:177], v143, off
	v_bfe_u32 v143, v125, 16, 1
	v_add3_u32 v143, v125, v143, s77
	v_mad_u64_u32 v[176:177], s[20:21], v172, s66, v[152:153]
	global_store_short_d16_hi v[176:177], v143, off
	v_bfe_u32 v143, v121, 16, 1
	v_add3_u32 v143, v121, v143, s77
	v_mad_u64_u32 v[176:177], s[20:21], v170, s66, v[152:153]
	global_store_short_d16_hi v[176:177], v143, off
	v_bfe_u32 v143, v126, 16, 1
	v_add3_u32 v143, v126, v143, s77
	v_mad_u64_u32 v[176:177], s[20:21], v169, s66, v[152:153]
	global_store_short_d16_hi v[176:177], v143, off
	v_bfe_u32 v143, v122, 16, 1
	v_add3_u32 v143, v122, v143, s77
	v_mad_u64_u32 v[176:177], s[20:21], v168, s66, v[152:153]
	global_store_short_d16_hi v[176:177], v143, off
	v_bfe_u32 v143, v127, 16, 1
	v_add3_u32 v143, v127, v143, s77
	v_mad_u64_u32 v[176:177], s[20:21], v167, s66, v[152:153]
	global_store_short_d16_hi v[176:177], v143, off
	v_bfe_u32 v143, v123, 16, 1
	v_add3_u32 v143, v123, v143, s77
	v_mad_u64_u32 v[176:177], s[20:21], v166, s66, v[152:153]
	global_store_short_d16_hi v[176:177], v143, off
	s_and_saveexec_b64 s[20:21], s[18:19]
	s_cbranch_execz .LBB0_1094
	v_lshl_add_u64 v[176:177], v[148:149], 2, s[44:45]
	v_lshl_add_u64 v[176:177], v[132:133], 2, v[176:177]
	global_store_dwordx4 v[176:177], v[124:127], off
	global_store_dwordx4 v[176:177], v[120:123], off offset:64

.LBB0_1346:
	ds_read_b128 v[148:151], v158
	ds_read_b128 v[152:155], v158 offset:1024
	ds_read_b128 v[162:165], v158 offset:2048
	ds_read_b128 v[166:169], v158 offset:3072
	s_add_u32 s20, s38, 0xfff80080
	s_addc_u32 s21, s39, -1
	s_cmp_eq_u32 s61, 28
	s_cselect_b32 s21, s17, s21
	s_cselect_b32 s20, s57, s20
	s_cselect_b32 s45, s15, s60
	s_cselect_b32 s44, s58, s59
	v_lshl_add_u64 v[190:191], s[38:39], 0, v[136:137]
	s_add_i32 m0, s37, 0xc000
	ds_read_b128 v[170:173], v159
	ds_read_b128 v[174:177], v159 offset:1024
	ds_read_b128 v[178:181], v159 offset:2048
	ds_read_b128 v[182:185], v159 offset:3072
	ds_read_b128 v[186:189], v159 offset:4096
	ds_read_b128 v[196:199], v159 offset:5120
	ds_read_b128 v[200:203], v159 offset:6144
	ds_read_b128 v[204:207], v159 offset:7168
	global_load_lds_dwordx4 v[190:191], off
	s_add_i32 m0, s37, 0xe000
	v_lshl_add_u64 v[190:191], s[38:39], 0, v[138:139]
	global_load_lds_dwordx4 v[190:191], off
	s_waitcnt lgkmcnt(8)
	s_waitcnt lgkmcnt(0)
	s_barrier
	s_setprio 1
	v_mfma_f32_16x16x32_bf16 v[124:127], v[148:151], v[170:173], v[124:127]
	v_mfma_f32_16x16x32_bf16 v[120:123], v[162:165], v[170:173], v[120:123]
	v_mfma_f32_16x16x32_bf16 v[108:111], v[148:151], v[178:181], v[108:111]
	v_mfma_f32_16x16x32_bf16 v[104:107], v[162:165], v[178:181], v[104:107]
	v_mfma_f32_16x16x32_bf16 v[92:95], v[148:151], v[186:189], v[92:95]
	v_mfma_f32_16x16x32_bf16 v[88:91], v[162:165], v[186:189], v[88:91]
	v_mfma_f32_16x16x32_bf16 v[76:79], v[148:151], v[200:203], v[76:79]
	v_mfma_f32_16x16x32_bf16 v[72:75], v[162:165], v[200:203], v[72:75]
	v_mfma_f32_16x16x32_bf16 v[124:127], v[152:155], v[174:177], v[124:127]
	v_mfma_f32_16x16x32_bf16 v[120:123], v[166:169], v[174:177], v[120:123]
	v_mfma_f32_16x16x32_bf16 v[108:111], v[152:155], v[182:185], v[108:111]
	v_mfma_f32_16x16x32_bf16 v[104:107], v[166:169], v[182:185], v[104:107]
	v_mfma_f32_16x16x32_bf16 v[92:95], v[152:155], v[196:199], v[92:95]
	v_mfma_f32_16x16x32_bf16 v[88:91], v[166:169], v[196:199], v[88:91]
	v_mfma_f32_16x16x32_bf16 v[76:79], v[152:155], v[204:207], v[76:79]
	v_mfma_f32_16x16x32_bf16 v[72:75], v[166:169], v[204:207], v[72:75]
	s_setprio 0
	s_barrier
	s_add_i32 s62, s53, s23
	v_lshl_add_u64 v[190:191], s[44:45], 0, v[132:133]
	s_mov_b32 m0, s62
	ds_read_b128 v[208:211], v160
	ds_read_b128 v[212:215], v160 offset:1024
	ds_read_b128 v[216:219], v160 offset:2048
	ds_read_b128 v[220:223], v160 offset:3072
	global_load_lds_dwordx4 v[190:191], off
	s_add_i32 m0, s62, 0x2000
	v_lshl_add_u64 v[224:225], s[44:45], 0, v[128:129]
	global_load_lds_dwordx4 v[224:225], off
	s_waitcnt lgkmcnt(0)
	s_barrier
	s_setprio 1
	v_mfma_f32_16x16x32_bf16 v[116:119], v[208:211], v[170:173], v[116:119]
	v_mfma_f32_16x16x32_bf16 v[112:115], v[216:219], v[170:173], v[112:115]
	v_mfma_f32_16x16x32_bf16 v[100:103], v[208:211], v[178:181], v[100:103]
	v_mfma_f32_16x16x32_bf16 v[96:99], v[216:219], v[178:181], v[96:99]
	v_mfma_f32_16x16x32_bf16 v[84:87], v[208:211], v[186:189], v[84:87]
	v_mfma_f32_16x16x32_bf16 v[80:83], v[216:219], v[186:189], v[80:83]
	v_mfma_f32_16x16x32_bf16 v[68:71], v[208:211], v[200:203], v[68:71]
	v_mfma_f32_16x16x32_bf16 v[64:67], v[216:219], v[200:203], v[64:67]
	v_mfma_f32_16x16x32_bf16 v[116:119], v[212:215], v[174:177], v[116:119]
	v_mfma_f32_16x16x32_bf16 v[112:115], v[220:223], v[174:177], v[112:115]
	v_mfma_f32_16x16x32_bf16 v[100:103], v[212:215], v[182:185], v[100:103]
	v_mfma_f32_16x16x32_bf16 v[96:99], v[220:223], v[182:185], v[96:99]
	v_mfma_f32_16x16x32_bf16 v[84:87], v[212:215], v[196:199], v[84:87]
	v_mfma_f32_16x16x32_bf16 v[80:83], v[220:223], v[196:199], v[80:83]
	v_mfma_f32_16x16x32_bf16 v[68:71], v[212:215], v[204:207], v[68:71]
	v_mfma_f32_16x16x32_bf16 v[64:67], v[220:223], v[204:207], v[64:67]
	s_setprio 0
	s_mov_b32 m0, s37
	v_lshl_add_u64 v[226:227], s[20:21], 0, v[134:135]
	s_barrier
	ds_read_b128 v[170:173], v159 offset:16384
	ds_read_b128 v[174:177], v159 offset:17408
	ds_read_b128 v[178:181], v159 offset:18432
	ds_read_b128 v[182:185], v159 offset:19456
	ds_read_b128 v[186:189], v159 offset:20480
	ds_read_b128 v[196:199], v159 offset:21504
	ds_read_b128 v[200:203], v159 offset:22528
	ds_read_b128 v[204:207], v159 offset:23552
	global_load_lds_dwordx4 v[226:227], off
	s_mov_b32 m0, s47
	v_lshl_add_u64 v[228:229], s[20:21], 0, v[130:131]
	global_load_lds_dwordx4 v[228:229], off
	s_waitcnt lgkmcnt(0)
	s_barrier
	s_setprio 1
	v_mfma_f32_16x16x32_bf16 v[60:63], v[148:151], v[170:173], v[60:63]
	v_mfma_f32_16x16x32_bf16 v[56:59], v[162:165], v[170:173], v[56:59]
	v_mfma_f32_16x16x32_bf16 v[44:47], v[148:151], v[178:181], v[44:47]
	v_mfma_f32_16x16x32_bf16 v[40:43], v[162:165], v[178:181], v[40:43]
	v_mfma_f32_16x16x32_bf16 v[28:31], v[148:151], v[186:189], v[28:31]
	v_mfma_f32_16x16x32_bf16 v[24:27], v[162:165], v[186:189], v[24:27]
	v_mfma_f32_16x16x32_bf16 v[12:15], v[148:151], v[200:203], v[12:15]
	v_mfma_f32_16x16x32_bf16 v[8:11], v[162:165], v[200:203], v[8:11]
	v_mfma_f32_16x16x32_bf16 v[60:63], v[152:155], v[174:177], v[60:63]
	v_mfma_f32_16x16x32_bf16 v[56:59], v[166:169], v[174:177], v[56:59]
	v_mfma_f32_16x16x32_bf16 v[44:47], v[152:155], v[182:185], v[44:47]
	v_mfma_f32_16x16x32_bf16 v[40:43], v[166:169], v[182:185], v[40:43]
	v_mfma_f32_16x16x32_bf16 v[28:31], v[152:155], v[196:199], v[28:31]
	v_mfma_f32_16x16x32_bf16 v[24:27], v[166:169], v[196:199], v[24:27]
	v_mfma_f32_16x16x32_bf16 v[12:15], v[152:155], v[204:207], v[12:15]
	v_mfma_f32_16x16x32_bf16 v[8:11], v[166:169], v[204:207], v[8:11]
	s_setprio 0
	s_barrier
	s_add_u32 s62, s44, 0x80000
	s_addc_u32 s63, s45, 0
	s_add_i32 s64, s55, s23
	s_mov_b32 m0, s64
	v_lshl_add_u64 v[148:149], s[62:63], 0, v[132:133]
	global_load_lds_dwordx4 v[148:149], off
	s_add_i32 m0, s64, 0x2000
	v_lshl_add_u64 v[148:149], s[62:63], 0, v[128:129]
	global_load_lds_dwordx4 v[148:149], off
	s_waitcnt vmcnt(6)
	s_barrier
	s_setprio 1
	v_mfma_f32_16x16x32_bf16 v[52:55], v[208:211], v[170:173], v[52:55]
	v_mfma_f32_16x16x32_bf16 v[48:51], v[216:219], v[170:173], v[48:51]
	v_mfma_f32_16x16x32_bf16 v[36:39], v[208:211], v[178:181], v[36:39]
	v_mfma_f32_16x16x32_bf16 v[32:35], v[216:219], v[178:181], v[32:35]
	v_mfma_f32_16x16x32_bf16 v[20:23], v[208:211], v[186:189], v[20:23]
	v_mfma_f32_16x16x32_bf16 v[16:19], v[216:219], v[186:189], v[16:19]
	v_mfma_f32_16x16x32_bf16 v[4:7], v[208:211], v[200:203], v[4:7]
	v_mfma_f32_16x16x32_bf16 v[0:3], v[216:219], v[200:203], v[0:3]
	v_mfma_f32_16x16x32_bf16 v[52:55], v[212:215], v[174:177], v[52:55]
	v_mfma_f32_16x16x32_bf16 v[48:51], v[220:223], v[174:177], v[48:51]
	v_mfma_f32_16x16x32_bf16 v[36:39], v[212:215], v[182:185], v[36:39]
	v_mfma_f32_16x16x32_bf16 v[32:35], v[220:223], v[182:185], v[32:35]
	v_mfma_f32_16x16x32_bf16 v[20:23], v[212:215], v[196:199], v[20:23]
	v_mfma_f32_16x16x32_bf16 v[16:19], v[220:223], v[196:199], v[16:19]
	v_mfma_f32_16x16x32_bf16 v[4:7], v[212:215], v[204:207], v[4:7]
	v_mfma_f32_16x16x32_bf16 v[0:3], v[220:223], v[204:207], v[0:3]
	s_setprio 0
	s_add_i32 s62, 0, 0x18000
	v_add_u32_e32 v161, s62, v147
	s_barrier
	ds_read_b128 v[148:151], v161
	ds_read_b128 v[152:155], v161 offset:1024
	ds_read_b128 v[162:165], v161 offset:2048
	ds_read_b128 v[166:169], v161 offset:3072
	s_add_u32 s20, s20, 0x80000
	s_addc_u32 s21, s21, 0
	s_mov_b32 m0, s48
	v_lshl_add_u64 v[208:209], s[20:21], 0, v[134:135]
	ds_read_b128 v[170:173], v159 offset:32768
	ds_read_b128 v[174:177], v159 offset:33792
	ds_read_b128 v[178:181], v159 offset:34816
	ds_read_b128 v[182:185], v159 offset:35840
	ds_read_b128 v[186:189], v159 offset:36864
	ds_read_b128 v[196:199], v159 offset:37888
	ds_read_b128 v[200:203], v159 offset:38912
	ds_read_b128 v[204:207], v159 offset:39936
	global_load_lds_dwordx4 v[208:209], off
	s_mov_b32 m0, s49
	v_lshl_add_u64 v[208:209], s[20:21], 0, v[130:131]
	global_load_lds_dwordx4 v[208:209], off
	s_waitcnt lgkmcnt(8)
	s_waitcnt lgkmcnt(0)
	s_barrier
	s_setprio 1
	v_mfma_f32_16x16x32_bf16 v[124:127], v[148:151], v[170:173], v[124:127]
	v_mfma_f32_16x16x32_bf16 v[120:123], v[162:165], v[170:173], v[120:123]
	v_mfma_f32_16x16x32_bf16 v[108:111], v[148:151], v[178:181], v[108:111]
	v_mfma_f32_16x16x32_bf16 v[104:107], v[162:165], v[178:181], v[104:107]
	v_mfma_f32_16x16x32_bf16 v[92:95], v[148:151], v[186:189], v[92:95]
	v_mfma_f32_16x16x32_bf16 v[88:91], v[162:165], v[186:189], v[88:91]
	v_mfma_f32_16x16x32_bf16 v[76:79], v[148:151], v[200:203], v[76:79]
	v_mfma_f32_16x16x32_bf16 v[72:75], v[162:165], v[200:203], v[72:75]
	v_mfma_f32_16x16x32_bf16 v[124:127], v[152:155], v[174:177], v[124:127]
	v_mfma_f32_16x16x32_bf16 v[120:123], v[166:169], v[174:177], v[120:123]
	v_mfma_f32_16x16x32_bf16 v[108:111], v[152:155], v[182:185], v[108:111]
	v_mfma_f32_16x16x32_bf16 v[104:107], v[166:169], v[182:185], v[104:107]
	v_mfma_f32_16x16x32_bf16 v[92:95], v[152:155], v[196:199], v[92:95]
	v_mfma_f32_16x16x32_bf16 v[88:91], v[166:169], v[196:199], v[88:91]
	v_mfma_f32_16x16x32_bf16 v[76:79], v[152:155], v[204:207], v[76:79]
	v_mfma_f32_16x16x32_bf16 v[72:75], v[166:169], v[204:207], v[72:75]
	s_setprio 0
	s_barrier
	s_add_i32 s63, 0, 0x1c000
	s_add_i32 s20, s62, s23
	v_add_u32_e32 v161, s63, v147
	v_lshl_add_u64 v[190:191], v[190:191], 0, s[10:11]
	s_mov_b32 m0, s20
	ds_read_b128 v[208:211], v161
	ds_read_b128 v[212:215], v161 offset:1024
	ds_read_b128 v[216:219], v161 offset:2048
	ds_read_b128 v[220:223], v161 offset:3072
	global_load_lds_dwordx4 v[190:191], off
	s_add_i32 m0, s20, 0x2000
	v_lshl_add_u64 v[190:191], v[224:225], 0, s[10:11]
	global_load_lds_dwordx4 v[190:191], off
	s_waitcnt lgkmcnt(0)
	s_barrier
	s_setprio 1
	v_mfma_f32_16x16x32_bf16 v[116:119], v[208:211], v[170:173], v[116:119]
	v_mfma_f32_16x16x32_bf16 v[112:115], v[216:219], v[170:173], v[112:115]
	v_mfma_f32_16x16x32_bf16 v[100:103], v[208:211], v[178:181], v[100:103]
	v_mfma_f32_16x16x32_bf16 v[96:99], v[216:219], v[178:181], v[96:99]
	v_mfma_f32_16x16x32_bf16 v[84:87], v[208:211], v[186:189], v[84:87]
	v_mfma_f32_16x16x32_bf16 v[80:83], v[216:219], v[186:189], v[80:83]
	v_mfma_f32_16x16x32_bf16 v[68:71], v[208:211], v[200:203], v[68:71]
	v_mfma_f32_16x16x32_bf16 v[64:67], v[216:219], v[200:203], v[64:67]
	v_mfma_f32_16x16x32_bf16 v[116:119], v[212:215], v[174:177], v[116:119]
	v_mfma_f32_16x16x32_bf16 v[112:115], v[220:223], v[174:177], v[112:115]
	v_mfma_f32_16x16x32_bf16 v[100:103], v[212:215], v[182:185], v[100:103]
	v_mfma_f32_16x16x32_bf16 v[96:99], v[220:223], v[182:185], v[96:99]
	v_mfma_f32_16x16x32_bf16 v[84:87], v[212:215], v[196:199], v[84:87]
	v_mfma_f32_16x16x32_bf16 v[80:83], v[220:223], v[196:199], v[80:83]
	v_mfma_f32_16x16x32_bf16 v[68:71], v[212:215], v[204:207], v[68:71]
	v_mfma_f32_16x16x32_bf16 v[64:67], v[220:223], v[204:207], v[64:67]
	s_setprio 0
	s_mov_b32 m0, s34
	v_lshl_add_u64 v[190:191], v[226:227], 0, s[10:11]
	s_barrier
	ds_read_b128 v[170:173], v159 offset:49152
	ds_read_b128 v[174:177], v159 offset:50176
	ds_read_b128 v[178:181], v159 offset:51200
	ds_read_b128 v[182:185], v159 offset:52224
	ds_read_b128 v[186:189], v159 offset:53248
	ds_read_b128 v[196:199], v159 offset:54272
	ds_read_b128 v[200:203], v159 offset:55296
	ds_read_b128 v[204:207], v159 offset:56320
	global_load_lds_dwordx4 v[190:191], off
	s_mov_b32 m0, s35
	v_lshl_add_u64 v[190:191], v[228:229], 0, s[10:11]
	global_load_lds_dwordx4 v[190:191], off
	s_waitcnt lgkmcnt(0)
	s_barrier
	s_setprio 1
	v_mfma_f32_16x16x32_bf16 v[60:63], v[148:151], v[170:173], v[60:63]
	v_mfma_f32_16x16x32_bf16 v[56:59], v[162:165], v[170:173], v[56:59]
	v_mfma_f32_16x16x32_bf16 v[44:47], v[148:151], v[178:181], v[44:47]
	v_mfma_f32_16x16x32_bf16 v[40:43], v[162:165], v[178:181], v[40:43]
	v_mfma_f32_16x16x32_bf16 v[28:31], v[148:151], v[186:189], v[28:31]
	v_mfma_f32_16x16x32_bf16 v[24:27], v[162:165], v[186:189], v[24:27]
	v_mfma_f32_16x16x32_bf16 v[12:15], v[148:151], v[200:203], v[12:15]
	v_mfma_f32_16x16x32_bf16 v[8:11], v[162:165], v[200:203], v[8:11]
	v_mfma_f32_16x16x32_bf16 v[60:63], v[152:155], v[174:177], v[60:63]
	v_mfma_f32_16x16x32_bf16 v[56:59], v[166:169], v[174:177], v[56:59]
	v_mfma_f32_16x16x32_bf16 v[44:47], v[152:155], v[182:185], v[44:47]
	v_mfma_f32_16x16x32_bf16 v[40:43], v[166:169], v[182:185], v[40:43]
	v_mfma_f32_16x16x32_bf16 v[28:31], v[152:155], v[196:199], v[28:31]
	v_mfma_f32_16x16x32_bf16 v[24:27], v[166:169], v[196:199], v[24:27]
	v_mfma_f32_16x16x32_bf16 v[12:15], v[152:155], v[204:207], v[12:15]
	v_mfma_f32_16x16x32_bf16 v[8:11], v[166:169], v[204:207], v[8:11]
	s_setprio 0
	s_barrier
	s_add_u32 s20, s44, 0x80080
	s_addc_u32 s21, s45, 0
	s_add_i32 s44, s63, s23
	s_mov_b32 m0, s44
	v_lshl_add_u64 v[148:149], s[20:21], 0, v[132:133]
	global_load_lds_dwordx4 v[148:149], off
	s_add_i32 m0, s44, 0x2000
	v_lshl_add_u64 v[148:149], s[20:21], 0, v[128:129]
	global_load_lds_dwordx4 v[148:149], off
	s_waitcnt vmcnt(6)
	s_barrier
	s_setprio 1
	v_mfma_f32_16x16x32_bf16 v[52:55], v[208:211], v[170:173], v[52:55]
	v_mfma_f32_16x16x32_bf16 v[48:51], v[216:219], v[170:173], v[48:51]
	v_mfma_f32_16x16x32_bf16 v[36:39], v[208:211], v[178:181], v[36:39]
	v_mfma_f32_16x16x32_bf16 v[32:35], v[216:219], v[178:181], v[32:35]
	v_mfma_f32_16x16x32_bf16 v[20:23], v[208:211], v[186:189], v[20:23]
	v_mfma_f32_16x16x32_bf16 v[16:19], v[216:219], v[186:189], v[16:19]
	v_mfma_f32_16x16x32_bf16 v[4:7], v[208:211], v[200:203], v[4:7]
	v_mfma_f32_16x16x32_bf16 v[0:3], v[216:219], v[200:203], v[0:3]
	v_mfma_f32_16x16x32_bf16 v[52:55], v[212:215], v[174:177], v[52:55]
	v_mfma_f32_16x16x32_bf16 v[48:51], v[220:223], v[174:177], v[48:51]
	v_mfma_f32_16x16x32_bf16 v[36:39], v[212:215], v[182:185], v[36:39]
	v_mfma_f32_16x16x32_bf16 v[32:35], v[220:223], v[182:185], v[32:35]
	v_mfma_f32_16x16x32_bf16 v[20:23], v[212:215], v[196:199], v[20:23]
	v_mfma_f32_16x16x32_bf16 v[16:19], v[220:223], v[196:199], v[16:19]
	v_mfma_f32_16x16x32_bf16 v[4:7], v[212:215], v[204:207], v[4:7]
	v_mfma_f32_16x16x32_bf16 v[0:3], v[220:223], v[204:207], v[0:3]
	s_setprio 0
	s_add_i32 s61, s61, 2
	s_add_u32 s38, s38, 0x100
	s_addc_u32 s39, s39, 0
	s_add_u32 s59, s59, 0x100
	s_addc_u32 s60, s60, 0
	s_cmp_gt_u32 s61, 29
	s_cbranch_scc1 .Lepi_last_c_out
	s_barrier
	s_branch .LBB0_1346

.LBB0_1402:
	ds_read_b128 v[154:157], v151
	ds_read_b128 v[158:161], v151 offset:1024
	ds_read_b128 v[162:165], v151 offset:2048
	ds_read_b128 v[166:169], v151 offset:3072
	s_add_u32 s20, s26, 0xfff80080
	s_addc_u32 s21, s27, -1
	s_cmp_eq_u32 s52, 28
	s_cselect_b32 s21, s15, s21
	s_cselect_b32 s20, s48, s20
	s_cselect_b32 s37, s11, s51
	s_cselect_b32 s36, s49, s50
	v_lshl_add_u64 v[148:149], s[26:27], 0, v[136:137]
	s_add_i32 m0, s25, 0xc000
	ds_read_b128 v[170:173], v152
	ds_read_b128 v[174:177], v152 offset:1024
	ds_read_b128 v[178:181], v152 offset:2048
	ds_read_b128 v[182:185], v152 offset:3072
	ds_read_b128 v[186:189], v152 offset:4096
	ds_read_b128 v[196:199], v152 offset:5120
	ds_read_b128 v[200:203], v152 offset:6144
	ds_read_b128 v[204:207], v152 offset:7168
	global_load_lds_dwordx4 v[148:149], off
	s_add_i32 m0, s25, 0xe000
	v_lshl_add_u64 v[148:149], s[26:27], 0, v[138:139]
	global_load_lds_dwordx4 v[148:149], off
	s_waitcnt lgkmcnt(8)
	s_waitcnt lgkmcnt(0)
	s_barrier
	s_setprio 1
	v_mfma_f32_16x16x32_bf16 v[124:127], v[154:157], v[170:173], v[124:127]
	v_mfma_f32_16x16x32_bf16 v[120:123], v[162:165], v[170:173], v[120:123]
	v_mfma_f32_16x16x32_bf16 v[108:111], v[154:157], v[178:181], v[108:111]
	v_mfma_f32_16x16x32_bf16 v[104:107], v[162:165], v[178:181], v[104:107]
	v_mfma_f32_16x16x32_bf16 v[92:95], v[154:157], v[186:189], v[92:95]
	v_mfma_f32_16x16x32_bf16 v[88:91], v[162:165], v[186:189], v[88:91]
	v_mfma_f32_16x16x32_bf16 v[76:79], v[154:157], v[200:203], v[76:79]
	v_mfma_f32_16x16x32_bf16 v[72:75], v[162:165], v[200:203], v[72:75]
	v_mfma_f32_16x16x32_bf16 v[124:127], v[158:161], v[174:177], v[124:127]
	v_mfma_f32_16x16x32_bf16 v[120:123], v[166:169], v[174:177], v[120:123]
	v_mfma_f32_16x16x32_bf16 v[108:111], v[158:161], v[182:185], v[108:111]
	v_mfma_f32_16x16x32_bf16 v[104:107], v[166:169], v[182:185], v[104:107]
	v_mfma_f32_16x16x32_bf16 v[92:95], v[158:161], v[196:199], v[92:95]
	v_mfma_f32_16x16x32_bf16 v[88:91], v[166:169], v[196:199], v[88:91]
	v_mfma_f32_16x16x32_bf16 v[76:79], v[158:161], v[204:207], v[76:79]
	v_mfma_f32_16x16x32_bf16 v[72:75], v[166:169], v[204:207], v[72:75]
	s_setprio 0
	s_barrier
	s_add_i32 s53, s46, s23
	v_lshl_add_u64 v[148:149], s[36:37], 0, v[132:133]
	s_mov_b32 m0, s53
	ds_read_b128 v[208:211], v153
	ds_read_b128 v[212:215], v153 offset:1024
	ds_read_b128 v[216:219], v153 offset:2048
	ds_read_b128 v[220:223], v153 offset:3072
	global_load_lds_dwordx4 v[148:149], off
	s_add_i32 m0, s53, 0x2000
	v_lshl_add_u64 v[190:191], s[36:37], 0, v[128:129]
	global_load_lds_dwordx4 v[190:191], off
	s_waitcnt lgkmcnt(0)
	s_barrier
	s_setprio 1
	v_mfma_f32_16x16x32_bf16 v[116:119], v[208:211], v[170:173], v[116:119]
	v_mfma_f32_16x16x32_bf16 v[112:115], v[216:219], v[170:173], v[112:115]
	v_mfma_f32_16x16x32_bf16 v[100:103], v[208:211], v[178:181], v[100:103]
	v_mfma_f32_16x16x32_bf16 v[96:99], v[216:219], v[178:181], v[96:99]
	v_mfma_f32_16x16x32_bf16 v[84:87], v[208:211], v[186:189], v[84:87]
	v_mfma_f32_16x16x32_bf16 v[80:83], v[216:219], v[186:189], v[80:83]
	v_mfma_f32_16x16x32_bf16 v[68:71], v[208:211], v[200:203], v[68:71]
	v_mfma_f32_16x16x32_bf16 v[64:67], v[216:219], v[200:203], v[64:67]
	v_mfma_f32_16x16x32_bf16 v[116:119], v[212:215], v[174:177], v[116:119]
	v_mfma_f32_16x16x32_bf16 v[112:115], v[220:223], v[174:177], v[112:115]
	v_mfma_f32_16x16x32_bf16 v[100:103], v[212:215], v[182:185], v[100:103]
	v_mfma_f32_16x16x32_bf16 v[96:99], v[220:223], v[182:185], v[96:99]
	v_mfma_f32_16x16x32_bf16 v[84:87], v[212:215], v[196:199], v[84:87]
	v_mfma_f32_16x16x32_bf16 v[80:83], v[220:223], v[196:199], v[80:83]
	v_mfma_f32_16x16x32_bf16 v[68:71], v[212:215], v[204:207], v[68:71]
	v_mfma_f32_16x16x32_bf16 v[64:67], v[220:223], v[204:207], v[64:67]
	s_setprio 0
	s_mov_b32 m0, s25
	v_lshl_add_u64 v[224:225], s[20:21], 0, v[134:135]
	s_barrier
	ds_read_b128 v[170:173], v152 offset:16384
	ds_read_b128 v[174:177], v152 offset:17408
	ds_read_b128 v[178:181], v152 offset:18432
	ds_read_b128 v[182:185], v152 offset:19456
	ds_read_b128 v[186:189], v152 offset:20480
	ds_read_b128 v[196:199], v152 offset:21504
	ds_read_b128 v[200:203], v152 offset:22528
	ds_read_b128 v[204:207], v152 offset:23552
	global_load_lds_dwordx4 v[224:225], off
	s_mov_b32 m0, s35
	v_lshl_add_u64 v[226:227], s[20:21], 0, v[130:131]
	global_load_lds_dwordx4 v[226:227], off
	s_waitcnt lgkmcnt(0)
	s_barrier
	s_setprio 1
	v_mfma_f32_16x16x32_bf16 v[60:63], v[154:157], v[170:173], v[60:63]
	v_mfma_f32_16x16x32_bf16 v[56:59], v[162:165], v[170:173], v[56:59]
	v_mfma_f32_16x16x32_bf16 v[44:47], v[154:157], v[178:181], v[44:47]
	v_mfma_f32_16x16x32_bf16 v[40:43], v[162:165], v[178:181], v[40:43]
	v_mfma_f32_16x16x32_bf16 v[28:31], v[154:157], v[186:189], v[28:31]
	v_mfma_f32_16x16x32_bf16 v[24:27], v[162:165], v[186:189], v[24:27]
	v_mfma_f32_16x16x32_bf16 v[12:15], v[154:157], v[200:203], v[12:15]
	v_mfma_f32_16x16x32_bf16 v[8:11], v[162:165], v[200:203], v[8:11]
	v_mfma_f32_16x16x32_bf16 v[60:63], v[158:161], v[174:177], v[60:63]
	v_mfma_f32_16x16x32_bf16 v[56:59], v[166:169], v[174:177], v[56:59]
	v_mfma_f32_16x16x32_bf16 v[44:47], v[158:161], v[182:185], v[44:47]
	v_mfma_f32_16x16x32_bf16 v[40:43], v[166:169], v[182:185], v[40:43]
	v_mfma_f32_16x16x32_bf16 v[28:31], v[158:161], v[196:199], v[28:31]
	v_mfma_f32_16x16x32_bf16 v[24:27], v[166:169], v[196:199], v[24:27]
	v_mfma_f32_16x16x32_bf16 v[12:15], v[158:161], v[204:207], v[12:15]
	v_mfma_f32_16x16x32_bf16 v[8:11], v[166:169], v[204:207], v[8:11]
	s_setprio 0
	s_barrier
	s_add_u32 s54, s36, 0x80000
	s_addc_u32 s55, s37, 0
	s_add_i32 s53, s47, s23
	s_mov_b32 m0, s53
	v_lshl_add_u64 v[154:155], s[54:55], 0, v[132:133]
	global_load_lds_dwordx4 v[154:155], off
	s_add_i32 m0, s53, 0x2000
	v_lshl_add_u64 v[154:155], s[54:55], 0, v[128:129]
	global_load_lds_dwordx4 v[154:155], off
	s_waitcnt vmcnt(6)
	s_barrier
	s_setprio 1
	v_mfma_f32_16x16x32_bf16 v[52:55], v[208:211], v[170:173], v[52:55]
	v_mfma_f32_16x16x32_bf16 v[48:51], v[216:219], v[170:173], v[48:51]
	v_mfma_f32_16x16x32_bf16 v[36:39], v[208:211], v[178:181], v[36:39]
	v_mfma_f32_16x16x32_bf16 v[32:35], v[216:219], v[178:181], v[32:35]
	v_mfma_f32_16x16x32_bf16 v[20:23], v[208:211], v[186:189], v[20:23]
	v_mfma_f32_16x16x32_bf16 v[16:19], v[216:219], v[186:189], v[16:19]
	v_mfma_f32_16x16x32_bf16 v[4:7], v[208:211], v[200:203], v[4:7]
	v_mfma_f32_16x16x32_bf16 v[0:3], v[216:219], v[200:203], v[0:3]
	v_mfma_f32_16x16x32_bf16 v[52:55], v[212:215], v[174:177], v[52:55]
	v_mfma_f32_16x16x32_bf16 v[48:51], v[220:223], v[174:177], v[48:51]
	v_mfma_f32_16x16x32_bf16 v[36:39], v[212:215], v[182:185], v[36:39]
	v_mfma_f32_16x16x32_bf16 v[32:35], v[220:223], v[182:185], v[32:35]
	v_mfma_f32_16x16x32_bf16 v[20:23], v[212:215], v[196:199], v[20:23]
	v_mfma_f32_16x16x32_bf16 v[16:19], v[220:223], v[196:199], v[16:19]
	v_mfma_f32_16x16x32_bf16 v[4:7], v[212:215], v[204:207], v[4:7]
	v_mfma_f32_16x16x32_bf16 v[0:3], v[220:223], v[204:207], v[0:3]
	s_setprio 0
	s_add_i32 s53, 0, 0x18000
	v_add_u32_e32 v166, s53, v147
	s_barrier
	ds_read_b128 v[154:157], v166
	ds_read_b128 v[158:161], v166 offset:1024
	ds_read_b128 v[162:165], v166 offset:2048
	ds_read_b128 v[166:169], v166 offset:3072
	s_add_u32 s20, s20, 0x80000
	s_addc_u32 s21, s21, 0
	s_mov_b32 m0, s38
	v_lshl_add_u64 v[208:209], s[20:21], 0, v[134:135]
	ds_read_b128 v[170:173], v152 offset:32768
	ds_read_b128 v[174:177], v152 offset:33792
	ds_read_b128 v[178:181], v152 offset:34816
	ds_read_b128 v[182:185], v152 offset:35840
	ds_read_b128 v[186:189], v152 offset:36864
	ds_read_b128 v[196:199], v152 offset:37888
	ds_read_b128 v[200:203], v152 offset:38912
	ds_read_b128 v[204:207], v152 offset:39936
	global_load_lds_dwordx4 v[208:209], off
	s_mov_b32 m0, s39
	v_lshl_add_u64 v[208:209], s[20:21], 0, v[130:131]
	global_load_lds_dwordx4 v[208:209], off
	s_waitcnt lgkmcnt(8)
	s_waitcnt lgkmcnt(0)
	s_barrier
	s_setprio 1
	v_mfma_f32_16x16x32_bf16 v[124:127], v[154:157], v[170:173], v[124:127]
	v_mfma_f32_16x16x32_bf16 v[120:123], v[162:165], v[170:173], v[120:123]
	v_mfma_f32_16x16x32_bf16 v[108:111], v[154:157], v[178:181], v[108:111]
	v_mfma_f32_16x16x32_bf16 v[104:107], v[162:165], v[178:181], v[104:107]
	v_mfma_f32_16x16x32_bf16 v[92:95], v[154:157], v[186:189], v[92:95]
	v_mfma_f32_16x16x32_bf16 v[88:91], v[162:165], v[186:189], v[88:91]
	v_mfma_f32_16x16x32_bf16 v[76:79], v[154:157], v[200:203], v[76:79]
	v_mfma_f32_16x16x32_bf16 v[72:75], v[162:165], v[200:203], v[72:75]
	v_mfma_f32_16x16x32_bf16 v[124:127], v[158:161], v[174:177], v[124:127]
	v_mfma_f32_16x16x32_bf16 v[120:123], v[166:169], v[174:177], v[120:123]
	v_mfma_f32_16x16x32_bf16 v[108:111], v[158:161], v[182:185], v[108:111]
	v_mfma_f32_16x16x32_bf16 v[104:107], v[166:169], v[182:185], v[104:107]
	v_mfma_f32_16x16x32_bf16 v[92:95], v[158:161], v[196:199], v[92:95]
	v_mfma_f32_16x16x32_bf16 v[88:91], v[166:169], v[196:199], v[88:91]
	v_mfma_f32_16x16x32_bf16 v[76:79], v[158:161], v[204:207], v[76:79]
	v_mfma_f32_16x16x32_bf16 v[72:75], v[166:169], v[204:207], v[72:75]
	s_setprio 0
	s_barrier
	s_add_i32 s54, 0, 0x1c000
	s_add_i32 s20, s53, s23
	v_add_u32_e32 v193, s54, v147
	v_lshl_add_u64 v[148:149], v[148:149], 0, s[8:9]
	s_mov_b32 m0, s20
	ds_read_b128 v[208:211], v193
	ds_read_b128 v[212:215], v193 offset:1024
	ds_read_b128 v[216:219], v193 offset:2048
	ds_read_b128 v[220:223], v193 offset:3072
	global_load_lds_dwordx4 v[148:149], off
	s_add_i32 m0, s20, 0x2000
	v_lshl_add_u64 v[148:149], v[190:191], 0, s[8:9]
	global_load_lds_dwordx4 v[148:149], off
	s_waitcnt lgkmcnt(0)
	s_barrier
	s_setprio 1
	v_mfma_f32_16x16x32_bf16 v[116:119], v[208:211], v[170:173], v[116:119]
	v_mfma_f32_16x16x32_bf16 v[112:115], v[216:219], v[170:173], v[112:115]
	v_mfma_f32_16x16x32_bf16 v[100:103], v[208:211], v[178:181], v[100:103]
	v_mfma_f32_16x16x32_bf16 v[96:99], v[216:219], v[178:181], v[96:99]
	v_mfma_f32_16x16x32_bf16 v[84:87], v[208:211], v[186:189], v[84:87]
	v_mfma_f32_16x16x32_bf16 v[80:83], v[216:219], v[186:189], v[80:83]
	v_mfma_f32_16x16x32_bf16 v[68:71], v[208:211], v[200:203], v[68:71]
	v_mfma_f32_16x16x32_bf16 v[64:67], v[216:219], v[200:203], v[64:67]
	v_mfma_f32_16x16x32_bf16 v[116:119], v[212:215], v[174:177], v[116:119]
	v_mfma_f32_16x16x32_bf16 v[112:115], v[220:223], v[174:177], v[112:115]
	v_mfma_f32_16x16x32_bf16 v[100:103], v[212:215], v[182:185], v[100:103]
	v_mfma_f32_16x16x32_bf16 v[96:99], v[220:223], v[182:185], v[96:99]
	v_mfma_f32_16x16x32_bf16 v[84:87], v[212:215], v[196:199], v[84:87]
	v_mfma_f32_16x16x32_bf16 v[80:83], v[220:223], v[196:199], v[80:83]
	v_mfma_f32_16x16x32_bf16 v[68:71], v[212:215], v[204:207], v[68:71]
	v_mfma_f32_16x16x32_bf16 v[64:67], v[220:223], v[204:207], v[64:67]
	s_setprio 0
	s_mov_b32 m0, s41
	v_lshl_add_u64 v[148:149], v[224:225], 0, s[8:9]
	s_barrier
	ds_read_b128 v[170:173], v152 offset:49152
	ds_read_b128 v[174:177], v152 offset:50176
	ds_read_b128 v[178:181], v152 offset:51200
	ds_read_b128 v[182:185], v152 offset:52224
	ds_read_b128 v[186:189], v152 offset:53248
	ds_read_b128 v[196:199], v152 offset:54272
	ds_read_b128 v[200:203], v152 offset:55296
	ds_read_b128 v[204:207], v152 offset:56320
	global_load_lds_dwordx4 v[148:149], off
	s_mov_b32 m0, s44
	v_lshl_add_u64 v[148:149], v[226:227], 0, s[8:9]
	global_load_lds_dwordx4 v[148:149], off
	s_waitcnt lgkmcnt(0)
	s_barrier
	s_setprio 1
	v_mfma_f32_16x16x32_bf16 v[60:63], v[154:157], v[170:173], v[60:63]
	v_mfma_f32_16x16x32_bf16 v[56:59], v[162:165], v[170:173], v[56:59]
	v_mfma_f32_16x16x32_bf16 v[44:47], v[154:157], v[178:181], v[44:47]
	v_mfma_f32_16x16x32_bf16 v[40:43], v[162:165], v[178:181], v[40:43]
	v_mfma_f32_16x16x32_bf16 v[28:31], v[154:157], v[186:189], v[28:31]
	v_mfma_f32_16x16x32_bf16 v[24:27], v[162:165], v[186:189], v[24:27]
	v_mfma_f32_16x16x32_bf16 v[12:15], v[154:157], v[200:203], v[12:15]
	v_mfma_f32_16x16x32_bf16 v[8:11], v[162:165], v[200:203], v[8:11]
	v_mfma_f32_16x16x32_bf16 v[60:63], v[158:161], v[174:177], v[60:63]
	v_mfma_f32_16x16x32_bf16 v[56:59], v[166:169], v[174:177], v[56:59]
	v_mfma_f32_16x16x32_bf16 v[44:47], v[158:161], v[182:185], v[44:47]
	v_mfma_f32_16x16x32_bf16 v[40:43], v[166:169], v[182:185], v[40:43]
	v_mfma_f32_16x16x32_bf16 v[28:31], v[158:161], v[196:199], v[28:31]
	v_mfma_f32_16x16x32_bf16 v[24:27], v[166:169], v[196:199], v[24:27]
	v_mfma_f32_16x16x32_bf16 v[12:15], v[158:161], v[204:207], v[12:15]
	v_mfma_f32_16x16x32_bf16 v[8:11], v[166:169], v[204:207], v[8:11]
	s_setprio 0
	s_barrier
	s_add_u32 s20, s36, 0x80080
	s_addc_u32 s21, s37, 0
	s_add_i32 s36, s54, s23
	s_mov_b32 m0, s36
	v_lshl_add_u64 v[148:149], s[20:21], 0, v[132:133]
	global_load_lds_dwordx4 v[148:149], off
	s_add_i32 m0, s36, 0x2000
	v_lshl_add_u64 v[148:149], s[20:21], 0, v[128:129]
	global_load_lds_dwordx4 v[148:149], off
	s_waitcnt vmcnt(6)
	s_barrier
	s_setprio 1
	v_mfma_f32_16x16x32_bf16 v[52:55], v[208:211], v[170:173], v[52:55]
	v_mfma_f32_16x16x32_bf16 v[48:51], v[216:219], v[170:173], v[48:51]
	v_mfma_f32_16x16x32_bf16 v[36:39], v[208:211], v[178:181], v[36:39]
	v_mfma_f32_16x16x32_bf16 v[32:35], v[216:219], v[178:181], v[32:35]
	v_mfma_f32_16x16x32_bf16 v[20:23], v[208:211], v[186:189], v[20:23]
	v_mfma_f32_16x16x32_bf16 v[16:19], v[216:219], v[186:189], v[16:19]
	v_mfma_f32_16x16x32_bf16 v[4:7], v[208:211], v[200:203], v[4:7]
	v_mfma_f32_16x16x32_bf16 v[0:3], v[216:219], v[200:203], v[0:3]
	v_mfma_f32_16x16x32_bf16 v[52:55], v[212:215], v[174:177], v[52:55]
	v_mfma_f32_16x16x32_bf16 v[48:51], v[220:223], v[174:177], v[48:51]
	v_mfma_f32_16x16x32_bf16 v[36:39], v[212:215], v[182:185], v[36:39]
	v_mfma_f32_16x16x32_bf16 v[32:35], v[220:223], v[182:185], v[32:35]
	v_mfma_f32_16x16x32_bf16 v[20:23], v[212:215], v[196:199], v[20:23]
	v_mfma_f32_16x16x32_bf16 v[16:19], v[220:223], v[196:199], v[16:19]
	v_mfma_f32_16x16x32_bf16 v[4:7], v[212:215], v[204:207], v[4:7]
	v_mfma_f32_16x16x32_bf16 v[0:3], v[220:223], v[204:207], v[0:3]
	s_setprio 0
	s_add_i32 s52, s52, 2
	s_add_u32 s26, s26, 0x100
	s_addc_u32 s27, s27, 0
	s_add_u32 s50, s50, 0x100
	s_addc_u32 s51, s51, 0
	s_cmp_gt_u32 s52, 29
	s_cbranch_scc1 .Ldup_last_mlpin1
	s_barrier
	s_branch .LBB0_1402

.LBB0_1433:
	ds_read_b128 v[148:151], v158
	ds_read_b128 v[152:155], v158 offset:1024
	ds_read_b128 v[162:165], v158 offset:2048
	ds_read_b128 v[166:169], v158 offset:3072
	s_add_u32 s20, s26, 0xffe00080
	s_addc_u32 s21, s27, -1
	s_cmpk_eq_i32 s53, 0x7c
	s_cselect_b32 s21, s15, s21
	s_cselect_b32 s20, s49, s20
	s_cselect_b32 s31, s11, s52
	s_cselect_b32 s30, s50, s51
	v_lshl_add_u64 v[204:205], s[26:27], 0, v[136:137]
	s_add_i32 m0, s25, 0xc000
	ds_read_b128 v[170:173], v159
	ds_read_b128 v[174:177], v159 offset:1024
	ds_read_b128 v[178:181], v159 offset:2048
	ds_read_b128 v[182:185], v159 offset:3072
	ds_read_b128 v[186:189], v159 offset:4096
	ds_read_b128 v[190:193], v159 offset:5120
	ds_read_b128 v[196:199], v159 offset:6144
	ds_read_b128 v[200:203], v159 offset:7168
	global_load_lds_dwordx4 v[204:205], off
	s_add_i32 m0, s25, 0xe000
	v_lshl_add_u64 v[204:205], s[26:27], 0, v[138:139]
	global_load_lds_dwordx4 v[204:205], off
	s_waitcnt lgkmcnt(8)
	s_waitcnt lgkmcnt(0)
	s_barrier
	s_setprio 1
	v_mfma_f32_16x16x32_bf16 v[124:127], v[148:151], v[170:173], v[124:127]
	v_mfma_f32_16x16x32_bf16 v[120:123], v[162:165], v[170:173], v[120:123]
	v_mfma_f32_16x16x32_bf16 v[108:111], v[148:151], v[178:181], v[108:111]
	v_mfma_f32_16x16x32_bf16 v[104:107], v[162:165], v[178:181], v[104:107]
	v_mfma_f32_16x16x32_bf16 v[92:95], v[148:151], v[186:189], v[92:95]
	v_mfma_f32_16x16x32_bf16 v[88:91], v[162:165], v[186:189], v[88:91]
	v_mfma_f32_16x16x32_bf16 v[76:79], v[148:151], v[196:199], v[76:79]
	v_mfma_f32_16x16x32_bf16 v[72:75], v[162:165], v[196:199], v[72:75]
	v_mfma_f32_16x16x32_bf16 v[124:127], v[152:155], v[174:177], v[124:127]
	v_mfma_f32_16x16x32_bf16 v[120:123], v[166:169], v[174:177], v[120:123]
	v_mfma_f32_16x16x32_bf16 v[108:111], v[152:155], v[182:185], v[108:111]
	v_mfma_f32_16x16x32_bf16 v[104:107], v[166:169], v[182:185], v[104:107]
	v_mfma_f32_16x16x32_bf16 v[92:95], v[152:155], v[190:193], v[92:95]
	v_mfma_f32_16x16x32_bf16 v[88:91], v[166:169], v[190:193], v[88:91]
	v_mfma_f32_16x16x32_bf16 v[76:79], v[152:155], v[200:203], v[76:79]
	v_mfma_f32_16x16x32_bf16 v[72:75], v[166:169], v[200:203], v[72:75]
	s_setprio 0
	s_barrier
	s_add_i32 s54, s45, s23
	v_lshl_add_u64 v[220:221], s[30:31], 0, v[132:133]
	s_mov_b32 m0, s54
	ds_read_b128 v[204:207], v160
	ds_read_b128 v[208:211], v160 offset:1024
	ds_read_b128 v[212:215], v160 offset:2048
	ds_read_b128 v[216:219], v160 offset:3072
	global_load_lds_dwordx4 v[220:221], off
	s_add_i32 m0, s54, 0x2000
	v_lshl_add_u64 v[222:223], s[30:31], 0, v[128:129]
	global_load_lds_dwordx4 v[222:223], off
	s_waitcnt lgkmcnt(0)
	s_barrier
	s_setprio 1
	v_mfma_f32_16x16x32_bf16 v[116:119], v[204:207], v[170:173], v[116:119]
	v_mfma_f32_16x16x32_bf16 v[112:115], v[212:215], v[170:173], v[112:115]
	v_mfma_f32_16x16x32_bf16 v[100:103], v[204:207], v[178:181], v[100:103]
	v_mfma_f32_16x16x32_bf16 v[96:99], v[212:215], v[178:181], v[96:99]
	v_mfma_f32_16x16x32_bf16 v[84:87], v[204:207], v[186:189], v[84:87]
	v_mfma_f32_16x16x32_bf16 v[80:83], v[212:215], v[186:189], v[80:83]
	v_mfma_f32_16x16x32_bf16 v[68:71], v[204:207], v[196:199], v[68:71]
	v_mfma_f32_16x16x32_bf16 v[64:67], v[212:215], v[196:199], v[64:67]
	v_mfma_f32_16x16x32_bf16 v[116:119], v[208:211], v[174:177], v[116:119]
	v_mfma_f32_16x16x32_bf16 v[112:115], v[216:219], v[174:177], v[112:115]
	v_mfma_f32_16x16x32_bf16 v[100:103], v[208:211], v[182:185], v[100:103]
	v_mfma_f32_16x16x32_bf16 v[96:99], v[216:219], v[182:185], v[96:99]
	v_mfma_f32_16x16x32_bf16 v[84:87], v[208:211], v[190:193], v[84:87]
	v_mfma_f32_16x16x32_bf16 v[80:83], v[216:219], v[190:193], v[80:83]
	v_mfma_f32_16x16x32_bf16 v[68:71], v[208:211], v[200:203], v[68:71]
	v_mfma_f32_16x16x32_bf16 v[64:67], v[216:219], v[200:203], v[64:67]
	s_setprio 0
	s_mov_b32 m0, s25
	v_lshl_add_u64 v[224:225], s[20:21], 0, v[134:135]
	s_barrier
	ds_read_b128 v[170:173], v159 offset:16384
	ds_read_b128 v[174:177], v159 offset:17408
	ds_read_b128 v[178:181], v159 offset:18432
	ds_read_b128 v[182:185], v159 offset:19456
	ds_read_b128 v[186:189], v159 offset:20480
	ds_read_b128 v[190:193], v159 offset:21504
	ds_read_b128 v[196:199], v159 offset:22528
	ds_read_b128 v[200:203], v159 offset:23552
	global_load_lds_dwordx4 v[224:225], off
	s_mov_b32 m0, s37
	v_lshl_add_u64 v[226:227], s[20:21], 0, v[130:131]
	global_load_lds_dwordx4 v[226:227], off
	s_waitcnt lgkmcnt(0)
	s_barrier
	s_setprio 1
	v_mfma_f32_16x16x32_bf16 v[60:63], v[148:151], v[170:173], v[60:63]
	v_mfma_f32_16x16x32_bf16 v[56:59], v[162:165], v[170:173], v[56:59]
	v_mfma_f32_16x16x32_bf16 v[44:47], v[148:151], v[178:181], v[44:47]
	v_mfma_f32_16x16x32_bf16 v[40:43], v[162:165], v[178:181], v[40:43]
	v_mfma_f32_16x16x32_bf16 v[28:31], v[148:151], v[186:189], v[28:31]
	v_mfma_f32_16x16x32_bf16 v[24:27], v[162:165], v[186:189], v[24:27]
	v_mfma_f32_16x16x32_bf16 v[12:15], v[148:151], v[196:199], v[12:15]
	v_mfma_f32_16x16x32_bf16 v[8:11], v[162:165], v[196:199], v[8:11]
	v_mfma_f32_16x16x32_bf16 v[60:63], v[152:155], v[174:177], v[60:63]
	v_mfma_f32_16x16x32_bf16 v[56:59], v[166:169], v[174:177], v[56:59]
	v_mfma_f32_16x16x32_bf16 v[44:47], v[152:155], v[182:185], v[44:47]
	v_mfma_f32_16x16x32_bf16 v[40:43], v[166:169], v[182:185], v[40:43]
	v_mfma_f32_16x16x32_bf16 v[28:31], v[152:155], v[190:193], v[28:31]
	v_mfma_f32_16x16x32_bf16 v[24:27], v[166:169], v[190:193], v[24:27]
	v_mfma_f32_16x16x32_bf16 v[12:15], v[152:155], v[200:203], v[12:15]
	v_mfma_f32_16x16x32_bf16 v[8:11], v[166:169], v[200:203], v[8:11]
	s_setprio 0
	s_barrier
	s_add_u32 s54, s30, 0x200000
	s_addc_u32 s55, s31, 0
	s_add_i32 s56, s47, s23
	s_mov_b32 m0, s56
	v_lshl_add_u64 v[148:149], s[54:55], 0, v[132:133]
	global_load_lds_dwordx4 v[148:149], off
	s_add_i32 m0, s56, 0x2000
	v_lshl_add_u64 v[148:149], s[54:55], 0, v[128:129]
	global_load_lds_dwordx4 v[148:149], off
	s_waitcnt vmcnt(6)
	s_barrier
	s_setprio 1
	v_mfma_f32_16x16x32_bf16 v[52:55], v[204:207], v[170:173], v[52:55]
	v_mfma_f32_16x16x32_bf16 v[48:51], v[212:215], v[170:173], v[48:51]
	v_mfma_f32_16x16x32_bf16 v[36:39], v[204:207], v[178:181], v[36:39]
	v_mfma_f32_16x16x32_bf16 v[32:35], v[212:215], v[178:181], v[32:35]
	v_mfma_f32_16x16x32_bf16 v[20:23], v[204:207], v[186:189], v[20:23]
	v_mfma_f32_16x16x32_bf16 v[16:19], v[212:215], v[186:189], v[16:19]
	v_mfma_f32_16x16x32_bf16 v[4:7], v[204:207], v[196:199], v[4:7]
	v_mfma_f32_16x16x32_bf16 v[0:3], v[212:215], v[196:199], v[0:3]
	v_mfma_f32_16x16x32_bf16 v[52:55], v[208:211], v[174:177], v[52:55]
	v_mfma_f32_16x16x32_bf16 v[48:51], v[216:219], v[174:177], v[48:51]
	v_mfma_f32_16x16x32_bf16 v[36:39], v[208:211], v[182:185], v[36:39]
	v_mfma_f32_16x16x32_bf16 v[32:35], v[216:219], v[182:185], v[32:35]
	v_mfma_f32_16x16x32_bf16 v[20:23], v[208:211], v[190:193], v[20:23]
	v_mfma_f32_16x16x32_bf16 v[16:19], v[216:219], v[190:193], v[16:19]
	v_mfma_f32_16x16x32_bf16 v[4:7], v[208:211], v[200:203], v[4:7]
	v_mfma_f32_16x16x32_bf16 v[0:3], v[216:219], v[200:203], v[0:3]
	s_setprio 0
	s_add_i32 s54, 0, 0x18000
	v_add_u32_e32 v161, s54, v147
	s_barrier
	ds_read_b128 v[148:151], v161
	ds_read_b128 v[152:155], v161 offset:1024
	ds_read_b128 v[162:165], v161 offset:2048
	ds_read_b128 v[166:169], v161 offset:3072
	s_add_u32 s20, s20, 0x200000
	s_addc_u32 s21, s21, 0
	s_mov_b32 m0, s38
	v_lshl_add_u64 v[204:205], s[20:21], 0, v[134:135]
	ds_read_b128 v[170:173], v159 offset:32768
	ds_read_b128 v[174:177], v159 offset:33792
	ds_read_b128 v[178:181], v159 offset:34816
	ds_read_b128 v[182:185], v159 offset:35840
	ds_read_b128 v[186:189], v159 offset:36864
	ds_read_b128 v[190:193], v159 offset:37888
	ds_read_b128 v[196:199], v159 offset:38912
	ds_read_b128 v[200:203], v159 offset:39936
	global_load_lds_dwordx4 v[204:205], off
	s_mov_b32 m0, s39
	v_lshl_add_u64 v[204:205], s[20:21], 0, v[130:131]
	global_load_lds_dwordx4 v[204:205], off
	s_waitcnt lgkmcnt(8)
	s_waitcnt lgkmcnt(0)
	s_barrier
	s_setprio 1
	v_mfma_f32_16x16x32_bf16 v[124:127], v[148:151], v[170:173], v[124:127]
	v_mfma_f32_16x16x32_bf16 v[120:123], v[162:165], v[170:173], v[120:123]
	v_mfma_f32_16x16x32_bf16 v[108:111], v[148:151], v[178:181], v[108:111]
	v_mfma_f32_16x16x32_bf16 v[104:107], v[162:165], v[178:181], v[104:107]
	v_mfma_f32_16x16x32_bf16 v[92:95], v[148:151], v[186:189], v[92:95]
	v_mfma_f32_16x16x32_bf16 v[88:91], v[162:165], v[186:189], v[88:91]
	v_mfma_f32_16x16x32_bf16 v[76:79], v[148:151], v[196:199], v[76:79]
	v_mfma_f32_16x16x32_bf16 v[72:75], v[162:165], v[196:199], v[72:75]
	v_mfma_f32_16x16x32_bf16 v[124:127], v[152:155], v[174:177], v[124:127]
	v_mfma_f32_16x16x32_bf16 v[120:123], v[166:169], v[174:177], v[120:123]
	v_mfma_f32_16x16x32_bf16 v[108:111], v[152:155], v[182:185], v[108:111]
	v_mfma_f32_16x16x32_bf16 v[104:107], v[166:169], v[182:185], v[104:107]
	v_mfma_f32_16x16x32_bf16 v[92:95], v[152:155], v[190:193], v[92:95]
	v_mfma_f32_16x16x32_bf16 v[88:91], v[166:169], v[190:193], v[88:91]
	v_mfma_f32_16x16x32_bf16 v[76:79], v[152:155], v[200:203], v[76:79]
	v_mfma_f32_16x16x32_bf16 v[72:75], v[166:169], v[200:203], v[72:75]
	s_setprio 0
	s_barrier
	s_add_i32 s55, 0, 0x1c000
	s_add_i32 s20, s54, s23
	v_add_u32_e32 v161, s55, v147
	v_lshl_add_u64 v[220:221], v[220:221], 0, s[8:9]
	s_mov_b32 m0, s20
	ds_read_b128 v[204:207], v161
	ds_read_b128 v[208:211], v161 offset:1024
	ds_read_b128 v[212:215], v161 offset:2048
	ds_read_b128 v[216:219], v161 offset:3072
	global_load_lds_dwordx4 v[220:221], off
	s_add_i32 m0, s20, 0x2000
	v_lshl_add_u64 v[220:221], v[222:223], 0, s[8:9]
	global_load_lds_dwordx4 v[220:221], off
	s_waitcnt lgkmcnt(0)
	s_barrier
	s_setprio 1
	v_mfma_f32_16x16x32_bf16 v[116:119], v[204:207], v[170:173], v[116:119]
	v_mfma_f32_16x16x32_bf16 v[112:115], v[212:215], v[170:173], v[112:115]
	v_mfma_f32_16x16x32_bf16 v[100:103], v[204:207], v[178:181], v[100:103]
	v_mfma_f32_16x16x32_bf16 v[96:99], v[212:215], v[178:181], v[96:99]
	v_mfma_f32_16x16x32_bf16 v[84:87], v[204:207], v[186:189], v[84:87]
	v_mfma_f32_16x16x32_bf16 v[80:83], v[212:215], v[186:189], v[80:83]
	v_mfma_f32_16x16x32_bf16 v[68:71], v[204:207], v[196:199], v[68:71]
	v_mfma_f32_16x16x32_bf16 v[64:67], v[212:215], v[196:199], v[64:67]
	v_mfma_f32_16x16x32_bf16 v[116:119], v[208:211], v[174:177], v[116:119]
	v_mfma_f32_16x16x32_bf16 v[112:115], v[216:219], v[174:177], v[112:115]
	v_mfma_f32_16x16x32_bf16 v[100:103], v[208:211], v[182:185], v[100:103]
	v_mfma_f32_16x16x32_bf16 v[96:99], v[216:219], v[182:185], v[96:99]
	v_mfma_f32_16x16x32_bf16 v[84:87], v[208:211], v[190:193], v[84:87]
	v_mfma_f32_16x16x32_bf16 v[80:83], v[216:219], v[190:193], v[80:83]
	v_mfma_f32_16x16x32_bf16 v[68:71], v[208:211], v[200:203], v[68:71]
	v_mfma_f32_16x16x32_bf16 v[64:67], v[216:219], v[200:203], v[64:67]
	s_setprio 0
	s_mov_b32 m0, s35
	v_lshl_add_u64 v[220:221], v[224:225], 0, s[8:9]
	s_barrier
	ds_read_b128 v[170:173], v159 offset:49152
	ds_read_b128 v[174:177], v159 offset:50176
	ds_read_b128 v[178:181], v159 offset:51200
	ds_read_b128 v[182:185], v159 offset:52224
	ds_read_b128 v[186:189], v159 offset:53248
	ds_read_b128 v[190:193], v159 offset:54272
	ds_read_b128 v[196:199], v159 offset:55296
	ds_read_b128 v[200:203], v159 offset:56320
	global_load_lds_dwordx4 v[220:221], off
	s_mov_b32 m0, s41
	v_lshl_add_u64 v[220:221], v[226:227], 0, s[8:9]
	global_load_lds_dwordx4 v[220:221], off
	s_waitcnt lgkmcnt(0)
	s_barrier
	s_setprio 1
	v_mfma_f32_16x16x32_bf16 v[60:63], v[148:151], v[170:173], v[60:63]
	v_mfma_f32_16x16x32_bf16 v[56:59], v[162:165], v[170:173], v[56:59]
	v_mfma_f32_16x16x32_bf16 v[44:47], v[148:151], v[178:181], v[44:47]
	v_mfma_f32_16x16x32_bf16 v[40:43], v[162:165], v[178:181], v[40:43]
	v_mfma_f32_16x16x32_bf16 v[28:31], v[148:151], v[186:189], v[28:31]
	v_mfma_f32_16x16x32_bf16 v[24:27], v[162:165], v[186:189], v[24:27]
	v_mfma_f32_16x16x32_bf16 v[12:15], v[148:151], v[196:199], v[12:15]
	v_mfma_f32_16x16x32_bf16 v[8:11], v[162:165], v[196:199], v[8:11]
	v_mfma_f32_16x16x32_bf16 v[60:63], v[152:155], v[174:177], v[60:63]
	v_mfma_f32_16x16x32_bf16 v[56:59], v[166:169], v[174:177], v[56:59]
	v_mfma_f32_16x16x32_bf16 v[44:47], v[152:155], v[182:185], v[44:47]
	v_mfma_f32_16x16x32_bf16 v[40:43], v[166:169], v[182:185], v[40:43]
	v_mfma_f32_16x16x32_bf16 v[28:31], v[152:155], v[190:193], v[28:31]
	v_mfma_f32_16x16x32_bf16 v[24:27], v[166:169], v[190:193], v[24:27]
	v_mfma_f32_16x16x32_bf16 v[12:15], v[152:155], v[200:203], v[12:15]
	v_mfma_f32_16x16x32_bf16 v[8:11], v[166:169], v[200:203], v[8:11]
	s_setprio 0
	s_barrier
	s_add_u32 s20, s30, 0x200080
	s_addc_u32 s21, s31, 0
	s_add_i32 s30, s55, s23
	s_mov_b32 m0, s30
	v_lshl_add_u64 v[148:149], s[20:21], 0, v[132:133]
	global_load_lds_dwordx4 v[148:149], off
	s_add_i32 m0, s30, 0x2000
	v_lshl_add_u64 v[148:149], s[20:21], 0, v[128:129]
	global_load_lds_dwordx4 v[148:149], off
	s_waitcnt vmcnt(6)
	s_barrier
	s_setprio 1
	v_mfma_f32_16x16x32_bf16 v[52:55], v[204:207], v[170:173], v[52:55]
	v_mfma_f32_16x16x32_bf16 v[48:51], v[212:215], v[170:173], v[48:51]
	v_mfma_f32_16x16x32_bf16 v[36:39], v[204:207], v[178:181], v[36:39]
	v_mfma_f32_16x16x32_bf16 v[32:35], v[212:215], v[178:181], v[32:35]
	v_mfma_f32_16x16x32_bf16 v[20:23], v[204:207], v[186:189], v[20:23]
	v_mfma_f32_16x16x32_bf16 v[16:19], v[212:215], v[186:189], v[16:19]
	v_mfma_f32_16x16x32_bf16 v[4:7], v[204:207], v[196:199], v[4:7]
	v_mfma_f32_16x16x32_bf16 v[0:3], v[212:215], v[196:199], v[0:3]
	v_mfma_f32_16x16x32_bf16 v[52:55], v[208:211], v[174:177], v[52:55]
	v_mfma_f32_16x16x32_bf16 v[48:51], v[216:219], v[174:177], v[48:51]
	v_mfma_f32_16x16x32_bf16 v[36:39], v[208:211], v[182:185], v[36:39]
	v_mfma_f32_16x16x32_bf16 v[32:35], v[216:219], v[182:185], v[32:35]
	v_mfma_f32_16x16x32_bf16 v[20:23], v[208:211], v[190:193], v[20:23]
	v_mfma_f32_16x16x32_bf16 v[16:19], v[216:219], v[190:193], v[16:19]
	v_mfma_f32_16x16x32_bf16 v[4:7], v[208:211], v[200:203], v[4:7]
	v_mfma_f32_16x16x32_bf16 v[0:3], v[216:219], v[200:203], v[0:3]
	s_setprio 0
	s_add_i32 s53, s53, 2
	s_add_u32 s26, s26, 0x100
	s_addc_u32 s27, s27, 0
	s_add_u32 s51, s51, 0x100
	s_addc_u32 s52, s52, 0
	s_cmpk_gt_u32 s53, 0x7d
	s_cbranch_scc1 .Lepi_last_mlpout1
	s_barrier
	s_branch .LBB0_1433
